# GLA mix_c: q/k rows of the next item also fetched at the previous item's output section (whole head free of HBM waits)
# baseline (speedup 1.0000x reference)
.LBB0_1593:
	s_waitcnt lgkmcnt(0)
	s_lshr_b32 s2, s2, 16
	s_and_b32 s2, 0xffff, s2
	s_cmp_lg_u32 s2, 0
	s_cselect_b64 s[12:13], -1, 0
	v_cndmask_b32_e64 v0, 0, 1, s[12:13]
	s_cmp_lg_u64 s[12:13], 0
	v_readfirstlane_b32 s2, v0
	s_addc_u32 s61, s22, 0
	s_lshl_b32 s12, s2, 1
	s_add_i32 s74, s89, s12
	s_lshl_b32 s12, s2, 7
	s_add_i32 s75, s88, s12
	s_lshl_b32 s12, s2, 3
	v_mov_b32_e32 v2, v1
	v_mov_b32_e32 v3, v1
	s_add_i32 s76, s83, s12
	s_lshl_b32 s12, s2, 6
	s_lshl_b32 s2, s2, 2
	v_mov_b32_e32 v0, v1
	v_mov_b64_e32 v[14:15], v[2:3]
	v_mov_b64_e32 v[18:19], v[2:3]
	s_waitcnt vmcnt(5)
	v_mov_b64_e32 v[30:31], v[2:3]
	s_waitcnt vmcnt(4)
	v_mov_b64_e32 v[34:35], v[2:3]
	s_add_i32 s77, s90, s12
	s_add_i32 s78, s91, s2
	s_mov_b32 s79, s72
	s_mov_b32 s80, s3
	s_mov_b32 s82, s97
	v_mov_b64_e32 v[12:13], v[0:1]
	v_mov_b64_e32 v[16:17], v[0:1]
	v_mov_b64_e32 v[28:29], v[0:1]
	v_mov_b64_e32 v[32:33], v[0:1]
	s_ashr_i32 s32, s82, 8
	s_lshl_b32 s32, s32, 12
	s_and_b32 s66, s82, 63
	s_lshl_b32 s66, s66, 6
	s_or_b32 s32, s32, s66
	s_bfe_u32 s66, s82, 0x20006
	s_lshl_b32 s66, s66, 7
	s_mov_b32 s100, s21
	s_mov_b32 s101, 0
	v_and_b32_e32 v230, 48, v204
	v_mov_b32_e32 v231, 0
	v_and_b32_e32 v232, 15, v204
	s_lshl_b32 s86, s66, 1
	s_add_u32 s86, s46, s86
	s_addc_u32 s87, s47, 0
	v_lshlrev_b32_e32 v236, 4, v232
	v_mov_b32_e32 v237, 0
	v_lshl_add_u64 v[234:235], v[236:237], 0, s[86:87]
	v_lshrrev_b32_e32 v233, 4, v204
	v_or_b32_e32 v233, s32, v233
	v_mad_u64_u32 v[236:237], s[98:99], v233, s33, v[234:235]
	global_load_dwordx4 v[188:191], v[236:237], off
	global_load_dwordx4 v[192:195], v[236:237], off offset:1024
	v_or_b32_e32 v233, 32, v233
	v_mad_u64_u32 v[236:237], s[98:99], v233, s33, v[234:235]
	global_load_dwordx4 v[196:199], v[236:237], off
	global_load_dwordx4 v[200:203], v[236:237], off offset:1024
	v_mov_b64_e32 v[234:235], s[46:47]
	v_or_b32_e32 v233, s32, v232
	v_mad_u64_u32 v[236:237], s[98:99], v233, s33, v[234:235]
	v_lshl_add_u64 v[236:237], v[236:237], 0, v[230:231]
	v_lshl_add_u64 v[236:237], v[236:237], 0, s[100:101]
	global_load_dwordx4 v[206:209], v[236:237], off offset:2048
	v_or_b32_e32 v233, 16, v232
	v_or_b32_e32 v233, s32, v233
	v_mad_u64_u32 v[236:237], s[98:99], v233, s33, v[234:235]
	v_lshl_add_u64 v[236:237], v[236:237], 0, v[230:231]
	v_lshl_add_u64 v[236:237], v[236:237], 0, s[100:101]
	global_load_dwordx4 v[210:213], v[236:237], off offset:2048
	v_or_b32_e32 v233, 32, v232
	v_or_b32_e32 v233, s32, v233
	v_mad_u64_u32 v[236:237], s[98:99], v233, s33, v[234:235]
	v_lshl_add_u64 v[236:237], v[236:237], 0, v[230:231]
	v_lshl_add_u64 v[236:237], v[236:237], 0, s[100:101]
	global_load_dwordx4 v[214:217], v[236:237], off offset:2048
	v_or_b32_e32 v233, 48, v232
	v_or_b32_e32 v233, s32, v233
	v_mad_u64_u32 v[236:237], s[98:99], v233, s33, v[234:235]
	v_lshl_add_u64 v[236:237], v[236:237], 0, v[230:231]
	v_lshl_add_u64 v[236:237], v[236:237], 0, s[100:101]
	global_load_dwordx4 v[218:221], v[236:237], off offset:2048
	v_lshrrev_b32_e32 v233, 6, v204
	v_lshlrev_b32_e32 v233, 4, v233
	v_or_b32_e32 v236, s66, v232
	v_add_u32_e32 v236, v236, v233
	v_lshlrev_b32_e32 v236, 5, v236
	v_and_b32_e32 v233, 16, v204
	v_add_u32_e32 v236, v236, v233
	v_mov_b32_e32 v237, 0
	v_lshl_add_u64 v[236:237], v[236:237], 0, s[50:51]
	v_mov_b32_e32 v222, 0
	v_mov_b32_e32 v223, 0
	v_mov_b32_e32 v224, 0
	v_mov_b32_e32 v225, 0
	v_and_b32_e32 v233, 63, v204
	v_cmp_gt_u32_e32 vcc, 32, v233
	s_and_saveexec_b64 s[70:71], vcc
	global_load_dwordx4 v[222:225], v[236:237], off
	s_or_b64 exec, exec, s[70:71]
	s_lshl_b32 s66, s66, 2
	s_add_u32 s86, s24, s66
	s_addc_u32 s87, s25, 0
	v_lshrrev_b32_e32 v233, 6, v204
	v_lshlrev_b32_e32 v236, 6, v233
	v_bfe_u32 v233, v204, 4, 2
	v_lshl_add_u32 v236, v233, 4, v236
	v_mov_b32_e32 v237, 0
	v_lshl_add_u64 v[236:237], v[236:237], 0, s[86:87]
	global_load_dwordx4 v[226:229], v[236:237], off
	s_waitcnt vmcnt(0)
	s_branch .LBB0_1596

.LBB0_1598:
	s_ashr_i32 s14, s82, 8
	s_and_b32 s67, s82, 63
	s_ashr_i32 s15, s14, 31
	s_bfe_u32 s84, s82, 0x20006
	v_mov_b32_e32 v185, v204
	s_lshl_b64 s[12:13], s[14:15], 12
	s_lshl_b32 s2, s67, 6
	s_or_b32 s12, s12, s2
	v_lshlrev_b32_e32 v0, 3, v185
	s_lshl_b32 s15, s84, 7
	s_lshl_b32 s2, s84, 8
	v_and_b32_e32 v158, 0x78, v0
	v_ashrrev_i32_e32 v168, 4, v185
	s_add_u32 s16, s46, s2
	s_addc_u32 s17, s47, 0
	v_lshlrev_b32_e32 v0, 1, v158
	v_ashrrev_i32_e32 v169, 31, v168
	v_lshl_add_u64 v[2:3], s[16:17], 0, v[0:1]
	v_lshl_add_u64 v[36:37], s[12:13], 0, v[168:169]
	v_add_u32_e32 v164, 32, v168
	v_mad_u64_u32 v[38:39], s[16:17], v36, s33, v[2:3]
	v_ashrrev_i32_e32 v165, 31, v164
	v_mad_i32_i24 v39, v37, s33, v39
	v_lshl_add_u64 v[36:37], s[12:13], 0, v[164:165]
	v_and_b32_e32 v131, 15, v185
	v_mad_u64_u32 v[2:3], s[16:17], v36, s33, v[2:3]
	v_mad_i32_i24 v3, v37, s33, v3
	v_or_b32_e32 v124, s12, v131
	v_mov_b64_e32 v[36:37], s[46:47]
	v_mad_u64_u32 v[134:135], s[16:17], v124, s33, v[36:37]
	v_or_b32_e32 v129, 16, v131
	v_mad_i32_i24 v135, s13, v174, v135
	v_and_b32_e32 v116, 48, v185
	v_mov_b32_e32 v117, v1
	v_or_b32_e32 v130, s12, v129
	global_load_dword v239, v[38:39], off
	v_mov_b32_e32 v96, v188
	v_mov_b32_e32 v97, v189
	v_mov_b32_e32 v98, v190
	v_mov_b32_e32 v99, v191
	global_load_dword v239, v[38:39], off offset:1024
	v_mov_b32_e32 v104, v192
	v_mov_b32_e32 v105, v193
	v_mov_b32_e32 v106, v194
	v_mov_b32_e32 v107, v195
	global_load_dword v239, v[2:3], off
	v_mov_b32_e32 v60, v196
	v_mov_b32_e32 v61, v197
	v_mov_b32_e32 v62, v198
	v_mov_b32_e32 v63, v199
	global_load_dword v239, v[2:3], off offset:1024
	v_mov_b32_e32 v100, v200
	v_mov_b32_e32 v101, v201
	v_mov_b32_e32 v102, v202
	v_mov_b32_e32 v103, v203
	v_lshl_add_u64 v[2:3], v[134:135], 0, v[116:117]
	v_mad_u64_u32 v[136:137], s[16:17], v130, s33, v[36:37]
	v_or_b32_e32 v177, 32, v131
	v_add_co_u32_e32 v2, vcc, s21, v2
	v_mad_i32_i24 v137, s13, v174, v137
	v_or_b32_e32 v128, s12, v177
	v_addc_co_u32_e32 v3, vcc, 0, v3, vcc
	v_lshl_add_u64 v[38:39], v[136:137], 0, v[116:117]
	v_mad_u64_u32 v[138:139], s[16:17], v128, s33, v[36:37]
	v_add_co_u32_e32 v38, vcc, s21, v38
	v_mad_i32_i24 v139, s13, v174, v139
	s_nop 0
	v_addc_co_u32_e32 v39, vcc, 0, v39, vcc
	global_load_dword v239, v[2:3], off offset:2048
	v_mov_b32_e32 v56, v206
	v_mov_b32_e32 v57, v207
	v_mov_b32_e32 v58, v208
	v_mov_b32_e32 v59, v209
	global_load_dword v239, v[38:39], off offset:2048
	v_mov_b32_e32 v52, v210
	v_mov_b32_e32 v53, v211
	v_mov_b32_e32 v54, v212
	v_mov_b32_e32 v55, v213
	v_lshl_add_u64 v[2:3], v[138:139], 0, v[116:117]
	v_add_co_u32_e32 v38, vcc, s21, v2
	v_ashrrev_i32_e32 v66, 6, v185
	s_nop 0
	v_addc_co_u32_e32 v39, vcc, 0, v3, vcc
	v_or_b32_e32 v3, 48, v131
	v_or_b32_e32 v2, s12, v3
	v_mad_u64_u32 v[140:141], s[16:17], v2, s33, v[36:37]
	v_mad_i32_i24 v141, s13, v174, v141
	v_lshl_add_u64 v[36:37], v[140:141], 0, v[116:117]
	v_add_co_u32_e32 v36, vcc, s21, v36
	v_lshlrev_b32_e32 v122, 4, v66
	s_nop 0
	v_addc_co_u32_e32 v37, vcc, 0, v37, vcc
	global_load_dword v239, v[38:39], off offset:2048
	v_mov_b32_e32 v44, v214
	v_mov_b32_e32 v45, v215
	v_mov_b32_e32 v46, v216
	v_mov_b32_e32 v47, v217
	s_nop 0
	global_load_dword v239, v[36:37], off offset:2048
	v_mov_b32_e32 v36, v218
	v_mov_b32_e32 v37, v219
	v_mov_b32_e32 v38, v220
	v_mov_b32_e32 v39, v221
	v_or_b32_e32 v40, s15, v131
	v_and_b32_e32 v133, 63, v185
	v_add_u32_e32 v48, v40, v122
	v_and_b32_e32 v40, 16, v185
	v_mov_b32_e32 v41, v1
	v_mov_b32_e32 v125, s13
	v_lshl_add_u64 v[50:51], s[50:51], 0, v[40:41]
	v_cmp_lt_u32_e32 vcc, 31, v133
	v_cmp_gt_u32_e64 s[12:13], 32, v133
	v_mov_b32_e32 v40, 0
	v_ashrrev_i32_e32 v49, 31, v48
	v_mov_b32_e32 v108, 0
	v_mov_b32_e32 v109, 0
	v_mov_b32_e32 v110, 0
	v_mov_b32_e32 v111, 0
	s_and_saveexec_b64 s[16:17], s[12:13]
	s_cbranch_execz .LBB0_1600
	v_lshlrev_b64 v[42:43], 5, v[48:49]
	v_lshl_add_u64 v[42:43], v[50:51], 0, v[42:43]
	global_load_dword v239, v[42:43], off
	v_mov_b32_e32 v108, v222
	v_mov_b32_e32 v109, v223
	v_mov_b32_e32 v110, v224
	v_mov_b32_e32 v111, v225

.LBB0_1626:
	s_or_b64 exec, exec, s[12:13]
	v_sub_u32_e32 v53, 0, v179
	v_sub_u32_e32 v54, 0, v202
	v_add_f32_e32 v52, v52, v40
	v_add_u32_e32 v53, v176, v53
	v_sub_u32_e32 v55, 0, v203
	ds_write_b32 v53, v52 offset:32256
	v_add_f32_e32 v51, v51, v40
	v_add_u32_e32 v52, v176, v54
	v_sub_u32_e32 v56, 0, v206
	ds_write_b32 v52, v51 offset:32256
	v_add_f32_e32 v50, v50, v40
	v_add_u32_e32 v51, v176, v55
	v_sub_u32_e32 v57, 0, v207
	ds_write_b32 v51, v50 offset:32256
	v_add_f32_e32 v49, v49, v40
	v_add_u32_e32 v50, v176, v56
	v_sub_u32_e32 v58, 0, v208
	ds_write_b32 v50, v49 offset:32256
	v_add_f32_e32 v48, v48, v40
	v_add_u32_e32 v49, v176, v57
	v_sub_u32_e32 v59, 0, v209
	ds_write_b32 v49, v48 offset:32256
	v_add_f32_e32 v47, v47, v40
	v_add_u32_e32 v48, v176, v58
	v_sub_u32_e32 v127, 0, v210
	ds_write_b32 v48, v47 offset:32256
	v_add_f32_e32 v46, v46, v40
	v_add_u32_e32 v47, v176, v59
	v_sub_u32_e32 v179, 0, v211
	ds_write_b32 v47, v46 offset:32256
	v_add_f32_e32 v45, v45, v40
	v_add_u32_e32 v46, v176, v127
	v_sub_u32_e32 v180, 0, v212
	ds_write_b32 v46, v45 offset:32256
	v_add_f32_e32 v44, v44, v40
	v_add_u32_e32 v45, v176, v179
	v_sub_u32_e32 v181, 0, v213
	ds_write_b32 v45, v44 offset:32256
	v_add_f32_e32 v43, v43, v40
	v_add_u32_e32 v44, v176, v180
	v_sub_u32_e32 v182, 0, v214
	ds_write_b32 v44, v43 offset:32256
	v_add_f32_e32 v42, v42, v40
	v_add_u32_e32 v43, v176, v181
	v_sub_u32_e32 v202, 0, v215
	ds_write_b32 v43, v42 offset:32256
	v_add_f32_e32 v41, v41, v40
	v_add_u32_e32 v42, v176, v182
	v_sub_u32_e32 v203, 0, v216
	ds_write_b32 v42, v41 offset:32256
	v_add_f32_e32 v39, v39, v40
	v_add_u32_e32 v41, v176, v202
	v_sub_u32_e32 v206, 0, v217
	ds_write_b32 v41, v39 offset:32256
	v_add_f32_e32 v38, v38, v40
	v_add_u32_e32 v39, v176, v203
	v_sub_u32_e32 v207, 0, v218
	ds_write_b32 v39, v38 offset:32256
	v_add_f32_e32 v37, v37, v40
	v_add_u32_e32 v38, v176, v206
	ds_write_b32 v38, v37 offset:32256
	v_add_f32_e32 v36, v36, v40
	v_add_u32_e32 v37, v176, v207
	ds_write_b32 v37, v36 offset:32256
	s_waitcnt lgkmcnt(0)
	s_barrier
	ds_read_b128 v[36:39], v186
	ds_read_b128 v[40:43], v184 offset:15872
	ds_read_b128 v[44:47], v184 offset:15888
	ds_read_b128 v[48:51], v186 offset:16
	s_waitcnt lgkmcnt(2)
	v_sub_f32_e32 v53, v40, v36
	v_mul_f32_e32 v53, 0x3fb8aa3b, v53
	v_sub_f32_e32 v55, v41, v37
	v_sub_f32_e32 v52, v36, v40
	v_exp_f32_e32 v54, v53
	v_sub_f32_e32 v53, v37, v41
	v_mul_f32_e32 v55, 0x3fb8aa3b, v55
	v_mul_f32_e32 v36, 0x3fb8aa3b, v36
	v_mul_f32_e32 v37, 0x3fb8aa3b, v37
	v_sub_f32_e32 v57, v42, v38
	v_exp_f32_e32 v55, v55
	v_exp_f32_e32 v36, v36
	v_exp_f32_e32 v37, v37
	v_mul_f32_e32 v57, 0x3fb8aa3b, v57
	v_sub_f32_e32 v59, v43, v39
	v_sub_f32_e32 v56, v38, v42
	v_exp_f32_e32 v58, v57
	v_mul_f32_e32 v38, 0x3fb8aa3b, v38
	v_sub_f32_e32 v57, v39, v43
	v_mul_f32_e32 v59, 0x3fb8aa3b, v59
	v_mul_f32_e32 v39, 0x3fb8aa3b, v39
	v_exp_f32_e32 v38, v38
	v_exp_f32_e32 v59, v59
	v_exp_f32_e32 v39, v39
	v_pk_mul_f32 v[54:55], v[54:55], v[156:157]
	v_pk_mul_f32 v[156:157], v[158:159], v[36:37]
	s_waitcnt lgkmcnt(0)
	v_sub_f32_e32 v37, v44, v48
	v_mul_f32_e32 v37, 0x3fb8aa3b, v37
	v_pk_mul_f32 v[58:59], v[58:59], v[154:155]
	v_pk_mul_f32 v[154:155], v[162:163], v[38:39]
	v_sub_f32_e32 v36, v48, v44
	v_exp_f32_e32 v38, v37
	v_sub_f32_e32 v37, v49, v45
	v_mul_f32_e32 v52, 0x3fb8aa3b, v52
	v_mul_f32_e32 v53, 0x3fb8aa3b, v53
	v_mul_f32_e32 v36, 0x3fb8aa3b, v36
	v_mul_f32_e32 v37, 0x3fb8aa3b, v37
	v_exp_f32_e32 v52, v52
	v_exp_f32_e32 v53, v53
	v_exp_f32_e32 v36, v36
	v_exp_f32_e32 v37, v37
	v_sub_f32_e32 v39, v45, v49
	v_mul_f32_e32 v39, 0x3fb8aa3b, v39
	v_exp_f32_e32 v39, v39
	v_pk_mul_f32 v[52:53], v[158:159], v[52:53]
	v_pk_mul_f32 v[158:159], v[160:161], v[36:37]
	v_sub_f32_e32 v37, v46, v50
	v_mul_f32_e32 v37, 0x3fb8aa3b, v37
	v_pk_mul_f32 v[152:153], v[38:39], v[152:153]
	v_mul_f32_e32 v36, 0x3fb8aa3b, v49
	v_exp_f32_e32 v38, v37
	v_mul_f32_e32 v37, 0x3fb8aa3b, v50
	v_exp_f32_e32 v49, v36
	v_sub_f32_e32 v36, v50, v46
	v_exp_f32_e32 v50, v37
	v_sub_f32_e32 v37, v51, v47
	v_mul_f32_e32 v56, 0x3fb8aa3b, v56
	v_mul_f32_e32 v57, 0x3fb8aa3b, v57
	v_mul_f32_e32 v48, 0x3fb8aa3b, v48
	v_mul_f32_e32 v36, 0x3fb8aa3b, v36
	v_mul_f32_e32 v37, 0x3fb8aa3b, v37
	v_sub_f32_e32 v39, v47, v51
	v_exp_f32_e32 v56, v56
	v_exp_f32_e32 v57, v57
	v_exp_f32_e32 v48, v48
	v_exp_f32_e32 v36, v36
	v_exp_f32_e32 v37, v37
	v_mul_f32_e32 v39, 0x3fb8aa3b, v39
	v_exp_f32_e32 v39, v39
	v_mul_f32_e32 v51, 0x3fb8aa3b, v51
	v_exp_f32_e32 v51, v51
	v_pk_mul_f32 v[56:57], v[162:163], v[56:57]
	v_pk_mul_f32 v[48:49], v[160:161], v[48:49]
	v_pk_mul_f32 v[160:161], v[166:167], v[36:37]
	v_pk_mul_f32 v[150:151], v[38:39], v[150:151]
	v_cvt_pk_bf16_f32 v36, v52, v53
	v_cvt_pk_bf16_f32 v37, v56, v57
	v_cvt_pk_bf16_f32 v38, v158, v159
	v_cvt_pk_bf16_f32 v39, v160, v161
	v_pk_mul_f32 v[50:51], v[166:167], v[50:51]
	ds_write_b128 v183, v[36:39] offset:32768
	v_cvt_pk_bf16_f32 v36, v54, v55
	v_cvt_pk_bf16_f32 v37, v58, v59
	v_cvt_pk_bf16_f32 v38, v152, v153
	v_cvt_pk_bf16_f32 v39, v150, v151
	ds_write_b128 v183, v[36:39] offset:50176
	v_cvt_pk_bf16_f32 v36, v156, v157
	v_cvt_pk_bf16_f32 v37, v154, v155
	v_cvt_pk_bf16_f32 v38, v48, v49
	v_cvt_pk_bf16_f32 v39, v50, v51
	ds_write_b128 v0, v[36:39]
	ds_read_b128 v[36:39], v189
	ds_read_b128 v[48:51], v189 offset:16
	s_waitcnt lgkmcnt(1)
	v_sub_f32_e32 v52, v36, v40
	v_sub_f32_e32 v40, v40, v36
	v_sub_f32_e32 v53, v37, v41
	v_sub_f32_e32 v41, v41, v37
	v_mul_f32_e32 v36, 0x3fb8aa3b, v36
	v_mul_f32_e32 v37, 0x3fb8aa3b, v37
	v_exp_f32_e32 v36, v36
	v_exp_f32_e32 v37, v37
	v_sub_f32_e32 v54, v38, v42
	v_sub_f32_e32 v42, v42, v38
	v_mul_f32_e32 v38, 0x3fb8aa3b, v38
	v_sub_f32_e32 v55, v39, v43
	v_sub_f32_e32 v43, v43, v39
	v_mul_f32_e32 v39, 0x3fb8aa3b, v39
	v_exp_f32_e32 v38, v38
	v_exp_f32_e32 v39, v39
	v_pk_mul_f32 v[56:57], v[164:165], v[36:37]
	s_waitcnt lgkmcnt(0)
	v_sub_f32_e32 v37, v44, v48
	v_mul_f32_e32 v37, 0x3fb8aa3b, v37
	v_pk_mul_f32 v[58:59], v[170:171], v[38:39]
	v_sub_f32_e32 v36, v48, v44
	v_exp_f32_e32 v38, v37
	v_sub_f32_e32 v37, v49, v45
	v_mul_f32_e32 v42, 0x3fb8aa3b, v42
	v_mul_f32_e32 v43, 0x3fb8aa3b, v43
	v_mul_f32_e32 v36, 0x3fb8aa3b, v36
	v_mul_f32_e32 v37, 0x3fb8aa3b, v37
	v_exp_f32_e32 v42, v42
	v_exp_f32_e32 v43, v43
	v_exp_f32_e32 v36, v36
	v_exp_f32_e32 v37, v37
	v_sub_f32_e32 v39, v45, v49
	v_mul_f32_e32 v39, 0x3fb8aa3b, v39
	v_exp_f32_e32 v39, v39
	v_pk_mul_f32 v[42:43], v[42:43], v[146:147]
	v_pk_mul_f32 v[146:147], v[168:169], v[36:37]
	v_sub_f32_e32 v37, v46, v50
	v_mul_f32_e32 v37, 0x3fb8aa3b, v37
	v_pk_mul_f32 v[144:145], v[38:39], v[144:145]
	v_mul_f32_e32 v36, 0x3fb8aa3b, v49
	v_exp_f32_e32 v38, v37
	v_mul_f32_e32 v37, 0x3fb8aa3b, v50
	v_exp_f32_e32 v45, v36
	v_sub_f32_e32 v36, v50, v46
	v_exp_f32_e32 v46, v37
	v_sub_f32_e32 v37, v51, v47
	v_mul_f32_e32 v52, 0x3fb8aa3b, v52
	v_mul_f32_e32 v53, 0x3fb8aa3b, v53
	v_mul_f32_e32 v54, 0x3fb8aa3b, v54
	v_mul_f32_e32 v55, 0x3fb8aa3b, v55
	v_mul_f32_e32 v36, 0x3fb8aa3b, v36
	v_mul_f32_e32 v37, 0x3fb8aa3b, v37
	v_sub_f32_e32 v39, v47, v51
	v_exp_f32_e32 v52, v52
	v_mul_f32_e32 v40, 0x3fb8aa3b, v40
	v_exp_f32_e32 v53, v53
	v_mul_f32_e32 v41, 0x3fb8aa3b, v41
	v_exp_f32_e32 v54, v54
	v_exp_f32_e32 v55, v55
	v_exp_f32_e32 v36, v36
	v_exp_f32_e32 v37, v37
	v_mul_f32_e32 v39, 0x3fb8aa3b, v39
	v_exp_f32_e32 v40, v40
	v_exp_f32_e32 v41, v41
	v_mul_f32_e32 v44, 0x3fb8aa3b, v48
	v_exp_f32_e32 v39, v39
	v_mul_f32_e32 v47, 0x3fb8aa3b, v51
	v_exp_f32_e32 v44, v44
	v_exp_f32_e32 v47, v47
	v_pk_mul_f32 v[52:53], v[164:165], v[52:53]
	v_pk_mul_f32 v[54:55], v[170:171], v[54:55]
	v_pk_mul_f32 v[48:49], v[172:173], v[36:37]
	v_pk_mul_f32 v[40:41], v[40:41], v[148:149]
	v_pk_mul_f32 v[50:51], v[38:39], v[142:143]
	v_cvt_pk_bf16_f32 v36, v52, v53
	v_cvt_pk_bf16_f32 v37, v54, v55
	v_cvt_pk_bf16_f32 v38, v146, v147
	v_cvt_pk_bf16_f32 v39, v48, v49
	v_pk_mul_f32 v[44:45], v[168:169], v[44:45]
	v_pk_mul_f32 v[46:47], v[172:173], v[46:47]
	ds_write_b128 v183, v[36:39] offset:41472
	v_cvt_pk_bf16_f32 v36, v40, v41
	v_cvt_pk_bf16_f32 v37, v42, v43
	v_cvt_pk_bf16_f32 v38, v144, v145
	v_cvt_pk_bf16_f32 v39, v50, v51
	ds_write_b128 v183, v[36:39] offset:58880
	v_cvt_pk_bf16_f32 v36, v56, v57
	v_cvt_pk_bf16_f32 v37, v58, v59
	v_cvt_pk_bf16_f32 v38, v44, v45
	v_cvt_pk_bf16_f32 v39, v46, v47
	ds_write_b128 v0, v[36:39] offset:8704
	s_waitcnt lgkmcnt(0)
	s_barrier
	ds_read_b128 v[36:39], v190 offset:50176
	ds_read_b128 v[40:43], v191 offset:32768
	ds_read_b128 v[44:47], v191 offset:32832
	ds_read_b128 v[48:51], v190 offset:50240
	s_waitcnt lgkmcnt(2)
	v_mfma_f32_16x16x32_bf16 v[36:39], v[36:39], v[40:43], 0
	ds_read_b128 v[52:55], v190 offset:54528
	ds_read_b128 v[56:59], v190 offset:54592
	v_mul_u32_u24_e32 v0, 0x90, v131
	v_add_u32_e32 v0, v188, v0
	s_waitcnt lgkmcnt(2)
	v_mfma_f32_16x16x32_bf16 v[36:39], v[48:51], v[44:47], v[36:39]
	ds_read_b128 v[48:51], v190 offset:50304
	s_waitcnt lgkmcnt(2)
	v_mfma_f32_16x16x32_bf16 v[40:43], v[52:55], v[40:43], 0
	s_waitcnt lgkmcnt(1)
	v_mfma_f32_16x16x32_bf16 v[40:43], v[56:59], v[44:47], v[40:43]
	ds_read_b128 v[44:47], v191 offset:32896
	ds_read_b128 v[52:55], v191 offset:32960
	ds_read_b128 v[56:59], v190 offset:50368
	s_waitcnt lgkmcnt(2)
	v_mfma_f32_16x16x32_bf16 v[36:39], v[48:51], v[44:47], v[36:39]
	ds_read_b128 v[48:51], v190 offset:54656
	ds_read_b128 v[142:145], v190 offset:54720
	s_waitcnt lgkmcnt(1)
	v_mfma_f32_16x16x32_bf16 v[40:43], v[48:51], v[44:47], v[40:43]
	v_or_b32_e32 v45, 1, v192
	v_cmp_le_i32_e32 vcc, v187, v45
	v_mul_u32_u24_e32 v44, 0x220, v194
	v_mfma_f32_16x16x32_bf16 v[36:39], v[56:59], v[52:55], v[36:39]
	v_add_u32_e32 v127, v185, v44
	s_waitcnt lgkmcnt(0)
	v_mfma_f32_16x16x32_bf16 v[40:43], v[142:145], v[52:55], v[40:43]
	s_nop 4
	v_cndmask_b32_e32 v37, 0, v37, vcc
	v_cmp_le_i32_e32 vcc, v187, v195
	v_cndmask_b32_e64 v36, v36, 0, s[18:19]
	v_cvt_pk_bf16_f32 v36, v36, v37
	v_cndmask_b32_e32 v38, 0, v38, vcc
	v_cmp_le_i32_e32 vcc, v187, v196
	s_nop 1
	v_cndmask_b32_e32 v39, 0, v39, vcc
	v_cmp_le_i32_e32 vcc, v187, v197
	v_cvt_pk_bf16_f32 v37, v38, v39
	s_nop 0
	v_cndmask_b32_e32 v38, 0, v40, vcc
	v_cmp_le_i32_e32 vcc, v187, v198
	s_nop 1
	v_cndmask_b32_e32 v39, 0, v41, vcc
	v_cmp_le_i32_e32 vcc, v187, v200
	v_cvt_pk_bf16_f32 v38, v38, v39
	s_nop 0
	v_cndmask_b32_e32 v40, 0, v42, vcc
	v_cmp_le_i32_e32 vcc, v187, v201
	s_nop 1
	v_cndmask_b32_e32 v41, 0, v43, vcc
	v_cvt_pk_bf16_f32 v39, v40, v41
	ds_write2_b64 v193, v[36:37], v[38:39] offset1:4
	s_waitcnt lgkmcnt(0)
	s_barrier
	ds_read_b64_tr_b16 v[38:39], v127 offset:2176
	ds_read_b64_tr_b16 v[36:37], v127
	ds_read_b64_tr_b16 v[42:43], v127 offset:2184
	ds_read_b64_tr_b16 v[40:41], v127 offset:8
	ds_read_b128 v[44:47], v0
	ds_read_b128 v[48:51], v0 offset:64
	s_waitcnt lgkmcnt(1)
	v_mfma_f32_16x16x32_bf16 v[52:55], v[36:39], v[44:47], v[88:91]
	ds_read_b128 v[56:59], v0 offset:2304
	s_nop 1
	ds_read_b128 v[88:91], v0 offset:2368
	v_mfma_f32_16x16x32_bf16 v[44:47], v[40:43], v[44:47], v[92:95]
	s_waitcnt lgkmcnt(1)
	v_mfma_f32_16x16x32_bf16 v[80:83], v[36:39], v[56:59], v[80:83]
	v_mfma_f32_16x16x32_bf16 v[56:59], v[40:43], v[56:59], v[84:87]
	s_nop 2
	ds_read_b128 v[84:87], v0 offset:4608
	ds_read_b128 v[92:95], v0 offset:4672
	s_waitcnt lgkmcnt(1)
	v_mfma_f32_16x16x32_bf16 v[68:71], v[36:39], v[84:87], v[68:71]
	v_mfma_f32_16x16x32_bf16 v[76:79], v[40:43], v[84:87], v[76:79]
	ds_read_b128 v[84:87], v0 offset:6912
	ds_read_b128 v[142:145], v0 offset:6976
	v_mul_u32_u24_e32 v0, 0x110, v131
	v_add_u32_e32 v0, v199, v0
	s_waitcnt lgkmcnt(1)
	v_mfma_f32_16x16x32_bf16 v[36:39], v[36:39], v[84:87], v[64:67]
	s_nop 2
	ds_read_b64_tr_b16 v[64:65], v127 offset:17408
	ds_read_b64_tr_b16 v[66:67], v127 offset:19584
	v_mfma_f32_16x16x32_bf16 v[40:43], v[40:43], v[84:87], v[60:63]
	s_nop 2
	ds_read_b64_tr_b16 v[62:63], v127 offset:19592
	ds_read_b64_tr_b16 v[60:61], v127 offset:17416
	s_waitcnt lgkmcnt(2)
	v_mfma_f32_16x16x32_bf16 v[52:55], v[64:67], v[48:51], v[52:55]
	s_waitcnt lgkmcnt(0)
	v_mfma_f32_16x16x32_bf16 v[44:47], v[60:63], v[48:51], v[44:47]
	v_mfma_f32_16x16x32_bf16 v[48:51], v[64:67], v[88:91], v[80:83]
	v_mfma_f32_16x16x32_bf16 v[56:59], v[60:63], v[88:91], v[56:59]
	v_mfma_f32_16x16x32_bf16 v[68:71], v[64:67], v[92:95], v[68:71]
	v_mfma_f32_16x16x32_bf16 v[76:79], v[60:63], v[92:95], v[76:79]
	v_mfma_f32_16x16x32_bf16 v[36:39], v[64:67], v[142:145], v[36:39]
	v_mfma_f32_16x16x32_bf16 v[40:43], v[60:63], v[142:145], v[40:43]
	ds_read_b128 v[60:63], v0
	ds_read_b128 v[64:67], v0 offset:64
	s_waitcnt vmcnt(7) lgkmcnt(1)
	v_mfma_f32_16x16x32_bf16 v[52:55], v[116:119], v[60:63], v[52:55]
	s_waitcnt vmcnt(3)
	v_mfma_f32_16x16x32_bf16 v[44:47], v[120:123], v[60:63], v[44:47]
	ds_read_b128 v[60:63], v0 offset:4352
	ds_read_b128 v[80:83], v0 offset:4416
	s_waitcnt lgkmcnt(1)
	v_mfma_f32_16x16x32_bf16 v[48:51], v[116:119], v[60:63], v[48:51]
	v_mfma_f32_16x16x32_bf16 v[56:59], v[120:123], v[60:63], v[56:59]
	ds_read_b128 v[60:63], v0 offset:8704
	ds_read_b128 v[84:87], v0 offset:8768
	s_waitcnt lgkmcnt(1)
	v_mfma_f32_16x16x32_bf16 v[68:71], v[116:119], v[60:63], v[68:71]
	v_mfma_f32_16x16x32_bf16 v[60:63], v[120:123], v[60:63], v[76:79]
	s_nop 2
	ds_read_b128 v[76:79], v0 offset:13056
	ds_read_b128 v[88:91], v0 offset:13120
	s_waitcnt lgkmcnt(1)
	v_mfma_f32_16x16x32_bf16 v[36:39], v[116:119], v[76:79], v[36:39]
	v_mfma_f32_16x16x32_bf16 v[40:43], v[120:123], v[76:79], v[40:43]
	v_mfma_f32_16x16x32_bf16 v[52:55], v[108:111], v[64:67], v[52:55]
	s_waitcnt vmcnt(2)
	v_mfma_f32_16x16x32_bf16 v[44:47], v[112:115], v[64:67], v[44:47]
	v_mfma_f32_16x16x32_bf16 v[48:51], v[108:111], v[80:83], v[48:51]
	v_mfma_f32_16x16x32_bf16 v[56:59], v[112:115], v[80:83], v[56:59]
	v_mfma_f32_16x16x32_bf16 v[64:67], v[108:111], v[84:87], v[68:71]
	v_mfma_f32_16x16x32_bf16 v[60:63], v[112:115], v[84:87], v[60:63]
	s_waitcnt lgkmcnt(0)
	v_mfma_f32_16x16x32_bf16 v[36:39], v[108:111], v[88:91], v[36:39]
	v_mfma_f32_16x16x32_bf16 v[40:43], v[112:115], v[88:91], v[40:43]
	ds_read_b128 v[68:71], v0 offset:128
	ds_read_b128 v[76:79], v0 offset:192
	s_waitcnt lgkmcnt(1)
	v_mfma_f32_16x16x32_bf16 v[52:55], v[100:103], v[68:71], v[52:55]
	s_waitcnt vmcnt(1)
	v_mfma_f32_16x16x32_bf16 v[44:47], v[104:107], v[68:71], v[44:47]
	ds_read_b128 v[68:71], v0 offset:4480
	ds_read_b128 v[84:87], v0 offset:4544
	s_waitcnt lgkmcnt(1)
	v_mfma_f32_16x16x32_bf16 v[48:51], v[100:103], v[68:71], v[48:51]
	v_mfma_f32_16x16x32_bf16 v[56:59], v[104:107], v[68:71], v[56:59]
	ds_read_b128 v[68:71], v0 offset:8832
	ds_read_b128 v[88:91], v0 offset:8896
	s_waitcnt lgkmcnt(1)
	v_mfma_f32_16x16x32_bf16 v[92:95], v[100:103], v[68:71], v[64:67]
	v_mfma_f32_16x16x32_bf16 v[68:71], v[104:107], v[68:71], v[60:63]
	s_nop 2
	ds_read_b128 v[60:63], v0 offset:13184
	ds_read_b128 v[108:111], v0 offset:13248
	s_waitcnt lgkmcnt(1)
	v_mfma_f32_16x16x32_bf16 v[36:39], v[100:103], v[60:63], v[36:39]
	v_mfma_f32_16x16x32_bf16 v[100:103], v[104:107], v[60:63], v[40:43]
	v_mfma_f32_16x16x32_bf16 v[80:83], v[72:75], v[76:79], v[52:55]
	s_waitcnt vmcnt(0)
	v_mfma_f32_16x16x32_bf16 v[76:79], v[96:99], v[76:79], v[44:47]
	v_mfma_f32_16x16x32_bf16 v[64:67], v[72:75], v[84:87], v[48:51]
	v_mfma_f32_16x16x32_bf16 v[60:63], v[96:99], v[84:87], v[56:59]
	v_mfma_f32_16x16x32_bf16 v[52:55], v[72:75], v[88:91], v[92:95]
	v_mfma_f32_16x16x32_bf16 v[48:51], v[96:99], v[88:91], v[68:71]
	s_waitcnt lgkmcnt(0)
	v_mfma_f32_16x16x32_bf16 v[40:43], v[72:75], v[108:111], v[36:39]
	v_mfma_f32_16x16x32_bf16 v[36:39], v[96:99], v[108:111], v[100:103]
	s_cmpk_gt_i32 s81, 0x3ff
	s_cbranch_scc1 .Lgca11_skip
	s_ashr_i32 s32, s81, 8
	s_lshl_b32 s32, s32, 12
	s_and_b32 s66, s81, 63
	s_lshl_b32 s66, s66, 6
	s_or_b32 s32, s32, s66
	s_bfe_u32 s66, s81, 0x20006
	s_lshl_b32 s66, s66, 7
	s_mov_b32 s100, s21
	s_mov_b32 s101, 0
	v_and_b32_e32 v230, 48, v204
	v_mov_b32_e32 v231, 0
	v_and_b32_e32 v232, 15, v204
	s_lshl_b32 s86, s66, 1
	s_add_u32 s86, s46, s86
	s_addc_u32 s87, s47, 0
	v_lshlrev_b32_e32 v236, 4, v232
	v_mov_b32_e32 v237, 0
	v_lshl_add_u64 v[234:235], v[236:237], 0, s[86:87]
	v_lshrrev_b32_e32 v233, 4, v204
	v_or_b32_e32 v233, s32, v233
	v_mad_u64_u32 v[236:237], s[98:99], v233, s33, v[234:235]
	global_load_dwordx4 v[188:191], v[236:237], off
	global_load_dwordx4 v[192:195], v[236:237], off offset:1024
	v_or_b32_e32 v233, 32, v233
	v_mad_u64_u32 v[236:237], s[98:99], v233, s33, v[234:235]
	global_load_dwordx4 v[196:199], v[236:237], off
	global_load_dwordx4 v[200:203], v[236:237], off offset:1024
	v_mov_b64_e32 v[234:235], s[46:47]
	v_or_b32_e32 v233, s32, v232
	v_mad_u64_u32 v[236:237], s[98:99], v233, s33, v[234:235]
	v_lshl_add_u64 v[236:237], v[236:237], 0, v[230:231]
	v_lshl_add_u64 v[236:237], v[236:237], 0, s[100:101]
	global_load_dwordx4 v[206:209], v[236:237], off offset:2048
	v_or_b32_e32 v233, 16, v232
	v_or_b32_e32 v233, s32, v233
	v_mad_u64_u32 v[236:237], s[98:99], v233, s33, v[234:235]
	v_lshl_add_u64 v[236:237], v[236:237], 0, v[230:231]
	v_lshl_add_u64 v[236:237], v[236:237], 0, s[100:101]
	global_load_dwordx4 v[210:213], v[236:237], off offset:2048
	v_or_b32_e32 v233, 32, v232
	v_or_b32_e32 v233, s32, v233
	v_mad_u64_u32 v[236:237], s[98:99], v233, s33, v[234:235]
	v_lshl_add_u64 v[236:237], v[236:237], 0, v[230:231]
	v_lshl_add_u64 v[236:237], v[236:237], 0, s[100:101]
	global_load_dwordx4 v[214:217], v[236:237], off offset:2048
	v_or_b32_e32 v233, 48, v232
	v_or_b32_e32 v233, s32, v233
	v_mad_u64_u32 v[236:237], s[98:99], v233, s33, v[234:235]
	v_lshl_add_u64 v[236:237], v[236:237], 0, v[230:231]
	v_lshl_add_u64 v[236:237], v[236:237], 0, s[100:101]
	global_load_dwordx4 v[218:221], v[236:237], off offset:2048
	v_lshrrev_b32_e32 v233, 6, v204
	v_lshlrev_b32_e32 v233, 4, v233
	v_or_b32_e32 v236, s66, v232
	v_add_u32_e32 v236, v236, v233
	v_lshlrev_b32_e32 v236, 5, v236
	v_and_b32_e32 v233, 16, v204
	v_add_u32_e32 v236, v236, v233
	v_mov_b32_e32 v237, 0
	v_lshl_add_u64 v[236:237], v[236:237], 0, s[50:51]
	v_mov_b32_e32 v222, 0
	v_mov_b32_e32 v223, 0
	v_mov_b32_e32 v224, 0
	v_mov_b32_e32 v225, 0
	v_and_b32_e32 v233, 63, v204
	v_cmp_gt_u32_e32 vcc, 32, v233
	s_and_saveexec_b64 s[70:71], vcc
	global_load_dwordx4 v[222:225], v[236:237], off
	s_or_b64 exec, exec, s[70:71]
	s_lshl_b32 s66, s66, 2
	s_add_u32 s86, s24, s66
	s_addc_u32 s87, s25, 0
	v_lshrrev_b32_e32 v233, 6, v204
	v_lshlrev_b32_e32 v236, 6, v233
	v_bfe_u32 v233, v204, 4, 2
	v_lshl_add_u32 v236, v233, 4, v236
	v_mov_b32_e32 v237, 0
	v_lshl_add_u64 v[236:237], v[236:237], 0, s[86:87]
	global_load_dwordx4 v[226:229], v[236:237], off

.LBB0_1637:
	s_ashr_i32 s14, s81, 8
	s_and_b32 s67, s81, 63
	s_ashr_i32 s15, s14, 31
	s_bfe_u32 s82, s81, 0x20006
	v_mov_b32_e32 v187, v204
	s_lshl_b64 s[12:13], s[14:15], 12
	s_lshl_b32 s2, s67, 6
	s_or_b32 s12, s12, s2
	v_lshlrev_b32_e32 v0, 3, v187
	s_lshl_b32 s15, s82, 7
	s_lshl_b32 s2, s82, 8
	v_and_b32_e32 v158, 0x78, v0
	v_ashrrev_i32_e32 v168, 4, v187
	s_add_u32 s16, s46, s2
	s_addc_u32 s17, s47, 0
	v_lshlrev_b32_e32 v0, 1, v158
	v_ashrrev_i32_e32 v169, 31, v168
	v_lshl_add_u64 v[2:3], s[16:17], 0, v[0:1]
	v_lshl_add_u64 v[36:37], s[12:13], 0, v[168:169]
	v_add_u32_e32 v164, 32, v168
	v_mad_u64_u32 v[38:39], s[16:17], v36, s33, v[2:3]
	v_ashrrev_i32_e32 v165, 31, v164
	v_mad_i32_i24 v39, v37, s33, v39
	v_lshl_add_u64 v[36:37], s[12:13], 0, v[164:165]
	v_mad_u64_u32 v[2:3], s[16:17], v36, s33, v[2:3]
	v_and_b32_e32 v131, 15, v187
	v_mad_i32_i24 v3, v37, s33, v3
	global_load_dword v239, v[38:39], off
	v_mov_b32_e32 v96, v188
	v_mov_b32_e32 v97, v189
	v_mov_b32_e32 v98, v190
	v_mov_b32_e32 v99, v191
	global_load_dword v239, v[38:39], off offset:1024
	v_mov_b32_e32 v104, v192
	v_mov_b32_e32 v105, v193
	v_mov_b32_e32 v106, v194
	v_mov_b32_e32 v107, v195
	global_load_dword v239, v[2:3], off
	v_mov_b32_e32 v60, v196
	v_mov_b32_e32 v61, v197
	v_mov_b32_e32 v62, v198
	v_mov_b32_e32 v63, v199
	global_load_dword v239, v[2:3], off offset:1024
	v_mov_b32_e32 v100, v200
	v_mov_b32_e32 v101, v201
	v_mov_b32_e32 v102, v202
	v_mov_b32_e32 v103, v203
	v_or_b32_e32 v2, s12, v131
	v_mov_b64_e32 v[36:37], s[46:47]
	v_mad_u64_u32 v[134:135], s[16:17], v2, s33, v[36:37]
	v_or_b32_e32 v129, 16, v131
	v_mad_i32_i24 v135, s13, v174, v135
	v_and_b32_e32 v116, 48, v187
	v_mov_b32_e32 v117, v1
	v_or_b32_e32 v130, s12, v129
	v_lshl_add_u64 v[38:39], v[134:135], 0, v[116:117]
	v_mad_u64_u32 v[136:137], s[16:17], v130, s33, v[36:37]
	v_or_b32_e32 v177, 32, v131
	v_add_co_u32_e32 v38, vcc, s21, v38
	v_mad_i32_i24 v137, s13, v174, v137
	v_or_b32_e32 v128, s12, v177
	v_addc_co_u32_e32 v39, vcc, 0, v39, vcc
	v_lshl_add_u64 v[40:41], v[136:137], 0, v[116:117]
	v_mad_u64_u32 v[138:139], s[16:17], v128, s33, v[36:37]
	v_or_b32_e32 v125, 48, v131
	v_add_co_u32_e32 v40, vcc, s21, v40
	v_mad_i32_i24 v139, s13, v174, v139
	v_or_b32_e32 v124, s12, v125
	v_addc_co_u32_e32 v41, vcc, 0, v41, vcc
	global_load_dword v239, v[38:39], off offset:2048
	v_mov_b32_e32 v56, v206
	v_mov_b32_e32 v57, v207
	v_mov_b32_e32 v58, v208
	v_mov_b32_e32 v59, v209
	global_load_dword v239, v[40:41], off offset:2048
	v_mov_b32_e32 v52, v210
	v_mov_b32_e32 v53, v211
	v_mov_b32_e32 v54, v212
	v_mov_b32_e32 v55, v213
	v_lshl_add_u64 v[38:39], v[138:139], 0, v[116:117]
	v_mad_u64_u32 v[140:141], s[16:17], v124, s33, v[36:37]
	v_add_co_u32_e32 v38, vcc, s21, v38
	v_mad_i32_i24 v141, s13, v174, v141
	s_nop 0
	v_addc_co_u32_e32 v39, vcc, 0, v39, vcc
	v_lshl_add_u64 v[36:37], v[140:141], 0, v[116:117]
	v_add_co_u32_e32 v36, vcc, s21, v36
	v_ashrrev_i32_e32 v66, 6, v187
	s_nop 0
	v_addc_co_u32_e32 v37, vcc, 0, v37, vcc
	global_load_dword v239, v[38:39], off offset:2048
	v_mov_b32_e32 v44, v214
	v_mov_b32_e32 v45, v215
	v_mov_b32_e32 v46, v216
	v_mov_b32_e32 v47, v217
	s_nop 0
	global_load_dword v239, v[36:37], off offset:2048
	v_mov_b32_e32 v36, v218
	v_mov_b32_e32 v37, v219
	v_mov_b32_e32 v38, v220
	v_mov_b32_e32 v39, v221
	v_lshlrev_b32_e32 v122, 4, v66
	v_or_b32_e32 v40, s15, v131
	v_and_b32_e32 v133, 63, v187
	v_add_u32_e32 v48, v40, v122
	v_and_b32_e32 v40, 16, v187
	v_mov_b32_e32 v41, v1
	v_mov_b32_e32 v3, s13
	v_lshl_add_u64 v[50:51], s[50:51], 0, v[40:41]
	v_cmp_lt_u32_e32 vcc, 31, v133
	v_cmp_gt_u32_e64 s[12:13], 32, v133
	v_mov_b32_e32 v40, 0
	v_ashrrev_i32_e32 v49, 31, v48
	v_mov_b32_e32 v108, 0
	v_mov_b32_e32 v109, 0
	v_mov_b32_e32 v110, 0
	v_mov_b32_e32 v111, 0
	s_and_saveexec_b64 s[16:17], s[12:13]
	s_cbranch_execz .LBB0_1639
	v_lshlrev_b64 v[42:43], 5, v[48:49]
	v_lshl_add_u64 v[42:43], v[50:51], 0, v[42:43]
	global_load_dword v239, v[42:43], off
	v_mov_b32_e32 v108, v222
	v_mov_b32_e32 v109, v223
	v_mov_b32_e32 v110, v224
	v_mov_b32_e32 v111, v225

.LBB0_1665:
	s_or_b64 exec, exec, s[12:13]
	v_sub_u32_e32 v53, 0, v181
	v_sub_u32_e32 v54, 0, v206
	v_add_f32_e32 v52, v52, v40
	v_add_u32_e32 v53, v180, v53
	v_sub_u32_e32 v55, 0, v207
	ds_write_b32 v53, v52 offset:32256
	v_add_f32_e32 v51, v51, v40
	v_add_u32_e32 v52, v180, v54
	v_sub_u32_e32 v56, 0, v208
	ds_write_b32 v52, v51 offset:32256
	v_add_f32_e32 v50, v50, v40
	v_add_u32_e32 v51, v180, v55
	v_sub_u32_e32 v57, 0, v209
	ds_write_b32 v51, v50 offset:32256
	v_add_f32_e32 v49, v49, v40
	v_add_u32_e32 v50, v180, v56
	v_sub_u32_e32 v58, 0, v210
	ds_write_b32 v50, v49 offset:32256
	v_add_f32_e32 v48, v48, v40
	v_add_u32_e32 v49, v180, v57
	v_sub_u32_e32 v59, 0, v211
	ds_write_b32 v49, v48 offset:32256
	v_add_f32_e32 v47, v47, v40
	v_add_u32_e32 v48, v180, v58
	v_sub_u32_e32 v127, 0, v212
	ds_write_b32 v48, v47 offset:32256
	v_add_f32_e32 v46, v46, v40
	v_add_u32_e32 v47, v180, v59
	v_sub_u32_e32 v181, 0, v213
	ds_write_b32 v47, v46 offset:32256
	v_add_f32_e32 v45, v45, v40
	v_add_u32_e32 v46, v180, v127
	v_sub_u32_e32 v182, 0, v214
	ds_write_b32 v46, v45 offset:32256
	v_add_f32_e32 v44, v44, v40
	v_add_u32_e32 v45, v180, v181
	v_sub_u32_e32 v183, 0, v215
	ds_write_b32 v45, v44 offset:32256
	v_add_f32_e32 v43, v43, v40
	v_add_u32_e32 v44, v180, v182
	v_sub_u32_e32 v184, 0, v216
	ds_write_b32 v44, v43 offset:32256
	v_add_f32_e32 v42, v42, v40
	v_add_u32_e32 v43, v180, v183
	v_sub_u32_e32 v206, 0, v217
	ds_write_b32 v43, v42 offset:32256
	v_add_f32_e32 v41, v41, v40
	v_add_u32_e32 v42, v180, v184
	v_sub_u32_e32 v207, 0, v218
	ds_write_b32 v42, v41 offset:32256
	v_add_f32_e32 v39, v39, v40
	v_add_u32_e32 v41, v180, v206
	v_sub_u32_e32 v208, 0, v219
	ds_write_b32 v41, v39 offset:32256
	v_add_f32_e32 v38, v38, v40
	v_add_u32_e32 v39, v180, v207
	v_sub_u32_e32 v209, 0, v220
	ds_write_b32 v39, v38 offset:32256
	v_add_f32_e32 v37, v37, v40
	v_add_u32_e32 v38, v180, v208
	ds_write_b32 v38, v37 offset:32256
	v_add_f32_e32 v36, v36, v40
	v_add_u32_e32 v37, v180, v209
	ds_write_b32 v37, v36 offset:32256
	s_waitcnt lgkmcnt(0)
	s_barrier
	ds_read_b128 v[36:39], v188
	ds_read_b128 v[40:43], v186 offset:15872
	ds_read_b128 v[44:47], v186 offset:15888
	ds_read_b128 v[48:51], v188 offset:16
	s_waitcnt lgkmcnt(2)
	v_sub_f32_e32 v53, v40, v36
	v_mul_f32_e32 v53, 0x3fb8aa3b, v53
	v_sub_f32_e32 v55, v41, v37
	v_sub_f32_e32 v52, v36, v40
	v_exp_f32_e32 v54, v53
	v_sub_f32_e32 v53, v37, v41
	v_mul_f32_e32 v55, 0x3fb8aa3b, v55
	v_mul_f32_e32 v36, 0x3fb8aa3b, v36
	v_mul_f32_e32 v37, 0x3fb8aa3b, v37
	v_sub_f32_e32 v57, v42, v38
	v_exp_f32_e32 v55, v55
	v_exp_f32_e32 v36, v36
	v_exp_f32_e32 v37, v37
	v_mul_f32_e32 v57, 0x3fb8aa3b, v57
	v_sub_f32_e32 v59, v43, v39
	v_sub_f32_e32 v56, v38, v42
	v_exp_f32_e32 v58, v57
	v_mul_f32_e32 v38, 0x3fb8aa3b, v38
	v_sub_f32_e32 v57, v39, v43
	v_mul_f32_e32 v59, 0x3fb8aa3b, v59
	v_mul_f32_e32 v39, 0x3fb8aa3b, v39
	v_exp_f32_e32 v38, v38
	v_exp_f32_e32 v59, v59
	v_exp_f32_e32 v39, v39
	v_pk_mul_f32 v[54:55], v[54:55], v[156:157]
	v_pk_mul_f32 v[156:157], v[158:159], v[36:37]
	s_waitcnt lgkmcnt(0)
	v_sub_f32_e32 v37, v44, v48
	v_mul_f32_e32 v37, 0x3fb8aa3b, v37
	v_pk_mul_f32 v[58:59], v[58:59], v[154:155]
	v_pk_mul_f32 v[154:155], v[162:163], v[38:39]
	v_sub_f32_e32 v36, v48, v44
	v_exp_f32_e32 v38, v37
	v_sub_f32_e32 v37, v49, v45
	v_mul_f32_e32 v52, 0x3fb8aa3b, v52
	v_mul_f32_e32 v53, 0x3fb8aa3b, v53
	v_mul_f32_e32 v36, 0x3fb8aa3b, v36
	v_mul_f32_e32 v37, 0x3fb8aa3b, v37
	v_exp_f32_e32 v52, v52
	v_exp_f32_e32 v53, v53
	v_exp_f32_e32 v36, v36
	v_exp_f32_e32 v37, v37
	v_sub_f32_e32 v39, v45, v49
	v_mul_f32_e32 v39, 0x3fb8aa3b, v39
	v_exp_f32_e32 v39, v39
	v_pk_mul_f32 v[52:53], v[158:159], v[52:53]
	v_pk_mul_f32 v[158:159], v[160:161], v[36:37]
	v_sub_f32_e32 v37, v46, v50
	v_mul_f32_e32 v37, 0x3fb8aa3b, v37
	v_pk_mul_f32 v[152:153], v[38:39], v[152:153]
	v_mul_f32_e32 v36, 0x3fb8aa3b, v49
	v_exp_f32_e32 v38, v37
	v_mul_f32_e32 v37, 0x3fb8aa3b, v50
	v_exp_f32_e32 v49, v36
	v_sub_f32_e32 v36, v50, v46
	v_exp_f32_e32 v50, v37
	v_sub_f32_e32 v37, v51, v47
	v_mul_f32_e32 v56, 0x3fb8aa3b, v56
	v_mul_f32_e32 v57, 0x3fb8aa3b, v57
	v_mul_f32_e32 v48, 0x3fb8aa3b, v48
	v_mul_f32_e32 v36, 0x3fb8aa3b, v36
	v_mul_f32_e32 v37, 0x3fb8aa3b, v37
	v_sub_f32_e32 v39, v47, v51
	v_exp_f32_e32 v56, v56
	v_exp_f32_e32 v57, v57
	v_exp_f32_e32 v48, v48
	v_exp_f32_e32 v36, v36
	v_exp_f32_e32 v37, v37
	v_mul_f32_e32 v39, 0x3fb8aa3b, v39
	v_exp_f32_e32 v39, v39
	v_mul_f32_e32 v51, 0x3fb8aa3b, v51
	v_exp_f32_e32 v51, v51
	v_pk_mul_f32 v[56:57], v[162:163], v[56:57]
	v_pk_mul_f32 v[48:49], v[160:161], v[48:49]
	v_pk_mul_f32 v[160:161], v[166:167], v[36:37]
	v_pk_mul_f32 v[150:151], v[38:39], v[150:151]
	v_cvt_pk_bf16_f32 v36, v52, v53
	v_cvt_pk_bf16_f32 v37, v56, v57
	v_cvt_pk_bf16_f32 v38, v158, v159
	v_cvt_pk_bf16_f32 v39, v160, v161
	v_pk_mul_f32 v[50:51], v[166:167], v[50:51]
	ds_write_b128 v185, v[36:39] offset:32768
	v_cvt_pk_bf16_f32 v36, v54, v55
	v_cvt_pk_bf16_f32 v37, v58, v59
	v_cvt_pk_bf16_f32 v38, v152, v153
	v_cvt_pk_bf16_f32 v39, v150, v151
	ds_write_b128 v185, v[36:39] offset:50176
	v_cvt_pk_bf16_f32 v36, v156, v157
	v_cvt_pk_bf16_f32 v37, v154, v155
	v_cvt_pk_bf16_f32 v38, v48, v49
	v_cvt_pk_bf16_f32 v39, v50, v51
	ds_write_b128 v0, v[36:39]
	ds_read_b128 v[36:39], v191
	ds_read_b128 v[48:51], v191 offset:16
	s_waitcnt lgkmcnt(1)
	v_sub_f32_e32 v52, v36, v40
	v_sub_f32_e32 v40, v40, v36
	v_sub_f32_e32 v53, v37, v41
	v_sub_f32_e32 v41, v41, v37
	v_mul_f32_e32 v36, 0x3fb8aa3b, v36
	v_mul_f32_e32 v37, 0x3fb8aa3b, v37
	v_exp_f32_e32 v36, v36
	v_exp_f32_e32 v37, v37
	v_sub_f32_e32 v54, v38, v42
	v_sub_f32_e32 v42, v42, v38
	v_mul_f32_e32 v38, 0x3fb8aa3b, v38
	v_sub_f32_e32 v55, v39, v43
	v_sub_f32_e32 v43, v43, v39
	v_mul_f32_e32 v39, 0x3fb8aa3b, v39
	v_exp_f32_e32 v38, v38
	v_exp_f32_e32 v39, v39
	v_pk_mul_f32 v[56:57], v[164:165], v[36:37]
	s_waitcnt lgkmcnt(0)
	v_sub_f32_e32 v37, v44, v48
	v_mul_f32_e32 v37, 0x3fb8aa3b, v37
	v_pk_mul_f32 v[58:59], v[170:171], v[38:39]
	v_sub_f32_e32 v36, v48, v44
	v_exp_f32_e32 v38, v37
	v_sub_f32_e32 v37, v49, v45
	v_mul_f32_e32 v42, 0x3fb8aa3b, v42
	v_mul_f32_e32 v43, 0x3fb8aa3b, v43
	v_mul_f32_e32 v36, 0x3fb8aa3b, v36
	v_mul_f32_e32 v37, 0x3fb8aa3b, v37
	v_exp_f32_e32 v42, v42
	v_exp_f32_e32 v43, v43
	v_exp_f32_e32 v36, v36
	v_exp_f32_e32 v37, v37
	v_sub_f32_e32 v39, v45, v49
	v_mul_f32_e32 v39, 0x3fb8aa3b, v39
	v_exp_f32_e32 v39, v39
	v_pk_mul_f32 v[42:43], v[42:43], v[146:147]
	v_pk_mul_f32 v[146:147], v[168:169], v[36:37]
	v_sub_f32_e32 v37, v46, v50
	v_mul_f32_e32 v37, 0x3fb8aa3b, v37
	v_pk_mul_f32 v[144:145], v[38:39], v[144:145]
	v_mul_f32_e32 v36, 0x3fb8aa3b, v49
	v_exp_f32_e32 v38, v37
	v_mul_f32_e32 v37, 0x3fb8aa3b, v50
	v_exp_f32_e32 v45, v36
	v_sub_f32_e32 v36, v50, v46
	v_exp_f32_e32 v46, v37
	v_sub_f32_e32 v37, v51, v47
	v_mul_f32_e32 v52, 0x3fb8aa3b, v52
	v_mul_f32_e32 v53, 0x3fb8aa3b, v53
	v_mul_f32_e32 v54, 0x3fb8aa3b, v54
	v_mul_f32_e32 v55, 0x3fb8aa3b, v55
	v_mul_f32_e32 v36, 0x3fb8aa3b, v36
	v_mul_f32_e32 v37, 0x3fb8aa3b, v37
	v_sub_f32_e32 v39, v47, v51
	v_exp_f32_e32 v52, v52
	v_mul_f32_e32 v40, 0x3fb8aa3b, v40
	v_exp_f32_e32 v53, v53
	v_mul_f32_e32 v41, 0x3fb8aa3b, v41
	v_exp_f32_e32 v54, v54
	v_exp_f32_e32 v55, v55
	v_exp_f32_e32 v36, v36
	v_exp_f32_e32 v37, v37
	v_mul_f32_e32 v39, 0x3fb8aa3b, v39
	v_exp_f32_e32 v40, v40
	v_exp_f32_e32 v41, v41
	v_mul_f32_e32 v44, 0x3fb8aa3b, v48
	v_exp_f32_e32 v39, v39
	v_mul_f32_e32 v47, 0x3fb8aa3b, v51
	v_exp_f32_e32 v44, v44
	v_exp_f32_e32 v47, v47
	v_pk_mul_f32 v[52:53], v[164:165], v[52:53]
	v_pk_mul_f32 v[54:55], v[170:171], v[54:55]
	v_pk_mul_f32 v[48:49], v[172:173], v[36:37]
	v_pk_mul_f32 v[40:41], v[40:41], v[148:149]
	v_pk_mul_f32 v[50:51], v[38:39], v[142:143]
	v_cvt_pk_bf16_f32 v36, v52, v53
	v_cvt_pk_bf16_f32 v37, v54, v55
	v_cvt_pk_bf16_f32 v38, v146, v147
	v_cvt_pk_bf16_f32 v39, v48, v49
	v_pk_mul_f32 v[44:45], v[168:169], v[44:45]
	v_pk_mul_f32 v[46:47], v[172:173], v[46:47]
	ds_write_b128 v185, v[36:39] offset:41472
	v_cvt_pk_bf16_f32 v36, v40, v41
	v_cvt_pk_bf16_f32 v37, v42, v43
	v_cvt_pk_bf16_f32 v38, v144, v145
	v_cvt_pk_bf16_f32 v39, v50, v51
	ds_write_b128 v185, v[36:39] offset:58880
	v_cvt_pk_bf16_f32 v36, v56, v57
	v_cvt_pk_bf16_f32 v37, v58, v59
	v_cvt_pk_bf16_f32 v38, v44, v45
	v_cvt_pk_bf16_f32 v39, v46, v47
	ds_write_b128 v0, v[36:39] offset:8704
	s_waitcnt lgkmcnt(0)
	s_barrier
	ds_read_b128 v[36:39], v192 offset:50176
	ds_read_b128 v[40:43], v193 offset:32768
	ds_read_b128 v[44:47], v193 offset:32832
	ds_read_b128 v[48:51], v192 offset:50240
	s_waitcnt lgkmcnt(2)
	v_mfma_f32_16x16x32_bf16 v[36:39], v[36:39], v[40:43], 0
	ds_read_b128 v[52:55], v192 offset:54528
	ds_read_b128 v[56:59], v192 offset:54592
	v_mul_u32_u24_e32 v0, 0x90, v131
	v_add_u32_e32 v0, v190, v0
	s_waitcnt lgkmcnt(2)
	v_mfma_f32_16x16x32_bf16 v[36:39], v[48:51], v[44:47], v[36:39]
	ds_read_b128 v[48:51], v192 offset:50304
	s_waitcnt lgkmcnt(2)
	v_mfma_f32_16x16x32_bf16 v[40:43], v[52:55], v[40:43], 0
	s_waitcnt lgkmcnt(1)
	v_mfma_f32_16x16x32_bf16 v[40:43], v[56:59], v[44:47], v[40:43]
	ds_read_b128 v[44:47], v193 offset:32896
	ds_read_b128 v[52:55], v193 offset:32960
	ds_read_b128 v[56:59], v192 offset:50368
	s_waitcnt lgkmcnt(2)
	v_mfma_f32_16x16x32_bf16 v[36:39], v[48:51], v[44:47], v[36:39]
	ds_read_b128 v[48:51], v192 offset:54656
	ds_read_b128 v[142:145], v192 offset:54720
	s_waitcnt lgkmcnt(1)
	v_mfma_f32_16x16x32_bf16 v[40:43], v[48:51], v[44:47], v[40:43]
	v_or_b32_e32 v45, 1, v194
	v_cmp_le_i32_e32 vcc, v189, v45
	v_mul_u32_u24_e32 v44, 0x220, v196
	v_mfma_f32_16x16x32_bf16 v[36:39], v[56:59], v[52:55], v[36:39]
	v_add_u32_e32 v127, v187, v44
	s_waitcnt lgkmcnt(0)
	v_mfma_f32_16x16x32_bf16 v[40:43], v[142:145], v[52:55], v[40:43]
	s_nop 4
	v_cndmask_b32_e32 v37, 0, v37, vcc
	v_cmp_le_i32_e32 vcc, v189, v197
	v_cndmask_b32_e64 v36, v36, 0, s[18:19]
	v_cvt_pk_bf16_f32 v36, v36, v37
	v_cndmask_b32_e32 v38, 0, v38, vcc
	v_cmp_le_i32_e32 vcc, v189, v198
	s_nop 1
	v_cndmask_b32_e32 v39, 0, v39, vcc
	v_cmp_le_i32_e32 vcc, v189, v199
	v_cvt_pk_bf16_f32 v37, v38, v39
	s_nop 0
	v_cndmask_b32_e32 v38, 0, v40, vcc
	v_cmp_le_i32_e32 vcc, v189, v200
	s_nop 1
	v_cndmask_b32_e32 v39, 0, v41, vcc
	v_cmp_le_i32_e32 vcc, v189, v202
	v_cvt_pk_bf16_f32 v38, v38, v39
	s_nop 0
	v_cndmask_b32_e32 v40, 0, v42, vcc
	v_cmp_le_i32_e32 vcc, v189, v203
	s_nop 1
	v_cndmask_b32_e32 v41, 0, v43, vcc
	v_cvt_pk_bf16_f32 v39, v40, v41
	ds_write2_b64 v195, v[36:37], v[38:39] offset1:4
	s_waitcnt lgkmcnt(0)
	s_barrier
	ds_read_b64_tr_b16 v[38:39], v127 offset:2176
	ds_read_b64_tr_b16 v[36:37], v127
	ds_read_b64_tr_b16 v[42:43], v127 offset:2184
	ds_read_b64_tr_b16 v[40:41], v127 offset:8
	ds_read_b128 v[44:47], v0
	ds_read_b128 v[48:51], v0 offset:64
	s_waitcnt lgkmcnt(1)
	v_mfma_f32_16x16x32_bf16 v[52:55], v[36:39], v[44:47], v[88:91]
	ds_read_b128 v[56:59], v0 offset:2304
	s_nop 1
	ds_read_b128 v[88:91], v0 offset:2368
	v_mfma_f32_16x16x32_bf16 v[44:47], v[40:43], v[44:47], v[92:95]
	s_waitcnt lgkmcnt(1)
	v_mfma_f32_16x16x32_bf16 v[80:83], v[36:39], v[56:59], v[80:83]
	v_mfma_f32_16x16x32_bf16 v[56:59], v[40:43], v[56:59], v[84:87]
	s_nop 2
	ds_read_b128 v[84:87], v0 offset:4608
	ds_read_b128 v[92:95], v0 offset:4672
	s_waitcnt lgkmcnt(1)
	v_mfma_f32_16x16x32_bf16 v[68:71], v[36:39], v[84:87], v[68:71]
	v_mfma_f32_16x16x32_bf16 v[76:79], v[40:43], v[84:87], v[76:79]
	ds_read_b128 v[84:87], v0 offset:6912
	ds_read_b128 v[142:145], v0 offset:6976
	v_mul_u32_u24_e32 v0, 0x110, v131
	v_add_u32_e32 v0, v201, v0
	s_waitcnt lgkmcnt(1)
	v_mfma_f32_16x16x32_bf16 v[36:39], v[36:39], v[84:87], v[64:67]
	s_nop 2
	ds_read_b64_tr_b16 v[64:65], v127 offset:17408
	ds_read_b64_tr_b16 v[66:67], v127 offset:19584
	v_mfma_f32_16x16x32_bf16 v[40:43], v[40:43], v[84:87], v[60:63]
	s_nop 2
	ds_read_b64_tr_b16 v[62:63], v127 offset:19592
	ds_read_b64_tr_b16 v[60:61], v127 offset:17416
	s_waitcnt lgkmcnt(2)
	v_mfma_f32_16x16x32_bf16 v[52:55], v[64:67], v[48:51], v[52:55]
	s_waitcnt lgkmcnt(0)
	v_mfma_f32_16x16x32_bf16 v[44:47], v[60:63], v[48:51], v[44:47]
	v_mfma_f32_16x16x32_bf16 v[48:51], v[64:67], v[88:91], v[80:83]
	v_mfma_f32_16x16x32_bf16 v[56:59], v[60:63], v[88:91], v[56:59]
	v_mfma_f32_16x16x32_bf16 v[68:71], v[64:67], v[92:95], v[68:71]
	v_mfma_f32_16x16x32_bf16 v[76:79], v[60:63], v[92:95], v[76:79]
	v_mfma_f32_16x16x32_bf16 v[36:39], v[64:67], v[142:145], v[36:39]
	v_mfma_f32_16x16x32_bf16 v[40:43], v[60:63], v[142:145], v[40:43]
	ds_read_b128 v[60:63], v0
	ds_read_b128 v[64:67], v0 offset:64
	s_waitcnt vmcnt(7) lgkmcnt(1)
	v_mfma_f32_16x16x32_bf16 v[52:55], v[116:119], v[60:63], v[52:55]
	s_waitcnt vmcnt(3)
	v_mfma_f32_16x16x32_bf16 v[44:47], v[120:123], v[60:63], v[44:47]
	ds_read_b128 v[60:63], v0 offset:4352
	ds_read_b128 v[80:83], v0 offset:4416
	s_waitcnt lgkmcnt(1)
	v_mfma_f32_16x16x32_bf16 v[48:51], v[116:119], v[60:63], v[48:51]
	v_mfma_f32_16x16x32_bf16 v[56:59], v[120:123], v[60:63], v[56:59]
	ds_read_b128 v[60:63], v0 offset:8704
	ds_read_b128 v[84:87], v0 offset:8768
	s_waitcnt lgkmcnt(1)
	v_mfma_f32_16x16x32_bf16 v[68:71], v[116:119], v[60:63], v[68:71]
	v_mfma_f32_16x16x32_bf16 v[60:63], v[120:123], v[60:63], v[76:79]
	s_nop 2
	ds_read_b128 v[76:79], v0 offset:13056
	ds_read_b128 v[88:91], v0 offset:13120
	s_waitcnt lgkmcnt(1)
	v_mfma_f32_16x16x32_bf16 v[36:39], v[116:119], v[76:79], v[36:39]
	v_mfma_f32_16x16x32_bf16 v[40:43], v[120:123], v[76:79], v[40:43]
	v_mfma_f32_16x16x32_bf16 v[52:55], v[108:111], v[64:67], v[52:55]
	s_waitcnt vmcnt(2)
	v_mfma_f32_16x16x32_bf16 v[44:47], v[112:115], v[64:67], v[44:47]
	v_mfma_f32_16x16x32_bf16 v[48:51], v[108:111], v[80:83], v[48:51]
	v_mfma_f32_16x16x32_bf16 v[56:59], v[112:115], v[80:83], v[56:59]
	v_mfma_f32_16x16x32_bf16 v[64:67], v[108:111], v[84:87], v[68:71]
	v_mfma_f32_16x16x32_bf16 v[60:63], v[112:115], v[84:87], v[60:63]
	s_waitcnt lgkmcnt(0)
	v_mfma_f32_16x16x32_bf16 v[36:39], v[108:111], v[88:91], v[36:39]
	v_mfma_f32_16x16x32_bf16 v[40:43], v[112:115], v[88:91], v[40:43]
	ds_read_b128 v[68:71], v0 offset:128
	ds_read_b128 v[76:79], v0 offset:192
	s_waitcnt lgkmcnt(1)
	v_mfma_f32_16x16x32_bf16 v[52:55], v[100:103], v[68:71], v[52:55]
	s_waitcnt vmcnt(1)
	v_mfma_f32_16x16x32_bf16 v[44:47], v[104:107], v[68:71], v[44:47]
	ds_read_b128 v[68:71], v0 offset:4480
	ds_read_b128 v[84:87], v0 offset:4544
	s_waitcnt lgkmcnt(1)
	v_mfma_f32_16x16x32_bf16 v[48:51], v[100:103], v[68:71], v[48:51]
	v_mfma_f32_16x16x32_bf16 v[56:59], v[104:107], v[68:71], v[56:59]
	ds_read_b128 v[68:71], v0 offset:8832
	ds_read_b128 v[88:91], v0 offset:8896
	s_waitcnt lgkmcnt(1)
	v_mfma_f32_16x16x32_bf16 v[92:95], v[100:103], v[68:71], v[64:67]
	v_mfma_f32_16x16x32_bf16 v[68:71], v[104:107], v[68:71], v[60:63]
	s_nop 2
	ds_read_b128 v[60:63], v0 offset:13184
	ds_read_b128 v[108:111], v0 offset:13248
	s_waitcnt lgkmcnt(1)
	v_mfma_f32_16x16x32_bf16 v[36:39], v[100:103], v[60:63], v[36:39]
	v_mfma_f32_16x16x32_bf16 v[100:103], v[104:107], v[60:63], v[40:43]
	v_mfma_f32_16x16x32_bf16 v[80:83], v[72:75], v[76:79], v[52:55]
	s_waitcnt vmcnt(0)
	v_mfma_f32_16x16x32_bf16 v[76:79], v[96:99], v[76:79], v[44:47]
	v_mfma_f32_16x16x32_bf16 v[64:67], v[72:75], v[84:87], v[48:51]
	v_mfma_f32_16x16x32_bf16 v[60:63], v[96:99], v[84:87], v[56:59]
	v_mfma_f32_16x16x32_bf16 v[52:55], v[72:75], v[88:91], v[92:95]
	v_mfma_f32_16x16x32_bf16 v[48:51], v[96:99], v[88:91], v[68:71]
	s_waitcnt lgkmcnt(0)
	v_mfma_f32_16x16x32_bf16 v[40:43], v[72:75], v[108:111], v[36:39]
	v_mfma_f32_16x16x32_bf16 v[36:39], v[96:99], v[108:111], v[100:103]
	s_add_i32 s85, s81, s61
	s_cmpk_gt_i32 s85, 0x3ff
	s_cbranch_scc1 .Lgcb11_skip
	s_ashr_i32 s32, s85, 8
	s_lshl_b32 s32, s32, 12
	s_and_b32 s66, s85, 63
	s_lshl_b32 s66, s66, 6
	s_or_b32 s32, s32, s66
	s_bfe_u32 s66, s85, 0x20006
	s_lshl_b32 s66, s66, 7
	s_mov_b32 s100, s21
	s_mov_b32 s101, 0
	v_and_b32_e32 v230, 48, v204
	v_mov_b32_e32 v231, 0
	v_and_b32_e32 v232, 15, v204
	s_lshl_b32 s86, s66, 1
	s_add_u32 s86, s46, s86
	s_addc_u32 s87, s47, 0
	v_lshlrev_b32_e32 v236, 4, v232
	v_mov_b32_e32 v237, 0
	v_lshl_add_u64 v[234:235], v[236:237], 0, s[86:87]
	v_lshrrev_b32_e32 v233, 4, v204
	v_or_b32_e32 v233, s32, v233
	v_mad_u64_u32 v[236:237], s[98:99], v233, s33, v[234:235]
	global_load_dwordx4 v[188:191], v[236:237], off
	global_load_dwordx4 v[192:195], v[236:237], off offset:1024
	v_or_b32_e32 v233, 32, v233
	v_mad_u64_u32 v[236:237], s[98:99], v233, s33, v[234:235]
	global_load_dwordx4 v[196:199], v[236:237], off
	global_load_dwordx4 v[200:203], v[236:237], off offset:1024
	v_mov_b64_e32 v[234:235], s[46:47]
	v_or_b32_e32 v233, s32, v232
	v_mad_u64_u32 v[236:237], s[98:99], v233, s33, v[234:235]
	v_lshl_add_u64 v[236:237], v[236:237], 0, v[230:231]
	v_lshl_add_u64 v[236:237], v[236:237], 0, s[100:101]
	global_load_dwordx4 v[206:209], v[236:237], off offset:2048
	v_or_b32_e32 v233, 16, v232
	v_or_b32_e32 v233, s32, v233
	v_mad_u64_u32 v[236:237], s[98:99], v233, s33, v[234:235]
	v_lshl_add_u64 v[236:237], v[236:237], 0, v[230:231]
	v_lshl_add_u64 v[236:237], v[236:237], 0, s[100:101]
	global_load_dwordx4 v[210:213], v[236:237], off offset:2048
	v_or_b32_e32 v233, 32, v232
	v_or_b32_e32 v233, s32, v233
	v_mad_u64_u32 v[236:237], s[98:99], v233, s33, v[234:235]
	v_lshl_add_u64 v[236:237], v[236:237], 0, v[230:231]
	v_lshl_add_u64 v[236:237], v[236:237], 0, s[100:101]
	global_load_dwordx4 v[214:217], v[236:237], off offset:2048
	v_or_b32_e32 v233, 48, v232
	v_or_b32_e32 v233, s32, v233
	v_mad_u64_u32 v[236:237], s[98:99], v233, s33, v[234:235]
	v_lshl_add_u64 v[236:237], v[236:237], 0, v[230:231]
	v_lshl_add_u64 v[236:237], v[236:237], 0, s[100:101]
	global_load_dwordx4 v[218:221], v[236:237], off offset:2048
	v_lshrrev_b32_e32 v233, 6, v204
	v_lshlrev_b32_e32 v233, 4, v233
	v_or_b32_e32 v236, s66, v232
	v_add_u32_e32 v236, v236, v233
	v_lshlrev_b32_e32 v236, 5, v236
	v_and_b32_e32 v233, 16, v204
	v_add_u32_e32 v236, v236, v233
	v_mov_b32_e32 v237, 0
	v_lshl_add_u64 v[236:237], v[236:237], 0, s[50:51]
	v_mov_b32_e32 v222, 0
	v_mov_b32_e32 v223, 0
	v_mov_b32_e32 v224, 0
	v_mov_b32_e32 v225, 0
	v_and_b32_e32 v233, 63, v204
	v_cmp_gt_u32_e32 vcc, 32, v233
	s_and_saveexec_b64 s[70:71], vcc
	global_load_dwordx4 v[222:225], v[236:237], off
	s_or_b64 exec, exec, s[70:71]
	s_lshl_b32 s66, s66, 2
	s_add_u32 s86, s24, s66
	s_addc_u32 s87, s25, 0
	v_lshrrev_b32_e32 v233, 6, v204
	v_lshlrev_b32_e32 v236, 6, v233
	v_bfe_u32 v233, v204, 4, 2
	v_lshl_add_u32 v236, v233, 4, v236
	v_mov_b32_e32 v237, 0
	v_lshl_add_u64 v[236:237], v[236:237], 0, s[86:87]
	global_load_dwordx4 v[226:229], v[236:237], off

.LBB0_1736:
	s_waitcnt lgkmcnt(0)
	s_add_u32 s16, s30, 0x7a00000
	s_addc_u32 s17, s31, 0
	s_add_u32 s18, s30, 0x32c0000
	s_addc_u32 s19, s31, 0
	s_add_u32 s34, s28, 0x4000000
	v_mov_b32_e32 v9, 0
	s_addc_u32 s35, s29, 0
	v_mov_b32_e32 v10, v9
	v_mov_b32_e32 v11, v9
	s_add_u32 s36, s30, 0x14a00000
	v_mov_b32_e32 v8, v9
	s_waitcnt vmcnt(0)
	v_mov_b64_e32 v[22:23], v[10:11]
	v_mov_b64_e32 v[26:27], v[10:11]
	v_mov_b64_e32 v[30:31], v[10:11]
	v_mov_b64_e32 v[34:35], v[10:11]
	s_addc_u32 s37, s31, 0
	s_mov_b32 s39, 0
	s_movk_i32 s0, 0x1a00
	s_mov_b32 s1, 0x7a00000
	s_movk_i32 s20, 0x1000
	s_movk_i32 s21, 0x220
	s_mov_b32 s33, 0xbfb8aa3b
	s_mov_b32 s40, 0x3f317218
	s_mov_b32 s42, 0x3d800000
	s_movk_i32 s41, 0x110
	s_movk_i32 s43, 0x90
	s_mov_b32 s44, 0x3db504f3
	s_mov_b32 s46, 0x3b800000
	s_mov_b32 s48, 0x358637bd
	s_mov_b32 s45, 0x800000
	v_mov_b32_e32 v174, 0x1a00
	s_mov_b32 s49, s97
	v_mov_b64_e32 v[20:21], v[8:9]
	v_mov_b64_e32 v[24:25], v[8:9]
	v_mov_b64_e32 v[28:29], v[8:9]
	v_mov_b64_e32 v[32:33], v[8:9]
	s_ashr_i32 s61, s49, 8
	s_add_i32 s61, s61, 4
	s_lshl_b32 s61, s61, 12
	s_and_b32 s62, s49, 63
	s_lshl_b32 s62, s62, 6
	s_or_b32 s61, s61, s62
	s_bfe_u32 s62, s49, 0x20006
	s_lshl_b32 s63, s62, 7
	s_mov_b32 s66, s20
	s_mov_b32 s67, 0
	v_and_b32_e32 v230, 48, v204
	v_mov_b32_e32 v231, 0
	v_and_b32_e32 v232, 15, v204
	s_lshl_b32 s78, s62, 8
	s_add_u32 s78, s16, s78
	s_addc_u32 s79, s17, 0
	v_lshlrev_b32_e32 v236, 4, v232
	v_mov_b32_e32 v237, 0
	v_lshl_add_u64 v[234:235], v[236:237], 0, s[78:79]
	v_lshrrev_b32_e32 v233, 4, v204
	v_or_b32_e32 v233, s61, v233
	v_mad_u64_u32 v[236:237], s[64:65], v233, s0, v[234:235]
	global_load_dwordx4 v[188:191], v[236:237], off
	global_load_dwordx4 v[192:195], v[236:237], off offset:1024
	v_or_b32_e32 v233, 32, v233
	v_mad_u64_u32 v[236:237], s[64:65], v233, s0, v[234:235]
	global_load_dwordx4 v[196:199], v[236:237], off
	global_load_dwordx4 v[200:203], v[236:237], off offset:1024
	v_mov_b64_e32 v[234:235], s[16:17]
	v_or_b32_e32 v233, s61, v232
	v_mad_u64_u32 v[236:237], s[64:65], v233, s0, v[234:235]
	v_lshl_add_u64 v[236:237], v[236:237], 0, v[230:231]
	v_lshl_add_u64 v[236:237], v[236:237], 0, s[66:67]
	global_load_dwordx4 v[206:209], v[236:237], off offset:2048
	v_or_b32_e32 v233, 16, v232
	v_or_b32_e32 v233, s61, v233
	v_mad_u64_u32 v[236:237], s[64:65], v233, s0, v[234:235]
	v_lshl_add_u64 v[236:237], v[236:237], 0, v[230:231]
	v_lshl_add_u64 v[236:237], v[236:237], 0, s[66:67]
	global_load_dwordx4 v[210:213], v[236:237], off offset:2048
	v_or_b32_e32 v233, 32, v232
	v_or_b32_e32 v233, s61, v233
	v_mad_u64_u32 v[236:237], s[64:65], v233, s0, v[234:235]
	v_lshl_add_u64 v[236:237], v[236:237], 0, v[230:231]
	v_lshl_add_u64 v[236:237], v[236:237], 0, s[66:67]
	global_load_dwordx4 v[214:217], v[236:237], off offset:2048
	v_or_b32_e32 v233, 48, v232
	v_or_b32_e32 v233, s61, v233
	v_mad_u64_u32 v[236:237], s[64:65], v233, s0, v[234:235]
	v_lshl_add_u64 v[236:237], v[236:237], 0, v[230:231]
	v_lshl_add_u64 v[236:237], v[236:237], 0, s[66:67]
	global_load_dwordx4 v[218:221], v[236:237], off offset:2048
	v_lshrrev_b32_e32 v233, 6, v204
	v_lshlrev_b32_e32 v233, 4, v233
	v_or_b32_e32 v236, s63, v232
	v_add_u32_e32 v236, v236, v233
	v_lshlrev_b32_e32 v236, 5, v236
	v_and_b32_e32 v233, 16, v204
	v_add_u32_e32 v236, v236, v233
	v_mov_b32_e32 v237, 0
	v_lshl_add_u64 v[236:237], v[236:237], 0, s[18:19]
	v_mov_b32_e32 v222, 0
	v_mov_b32_e32 v223, 0
	v_mov_b32_e32 v224, 0
	v_mov_b32_e32 v225, 0
	v_and_b32_e32 v233, 63, v204
	v_cmp_gt_u32_e32 vcc, 32, v233
	s_and_saveexec_b64 s[70:71], vcc
	global_load_dwordx4 v[222:225], v[236:237], off
	s_or_b64 exec, exec, s[70:71]
	s_lshl_b32 s63, s63, 2
	s_add_u32 s74, s24, s63
	s_addc_u32 s75, s25, 0
	v_lshrrev_b32_e32 v233, 6, v204
	v_lshlrev_b32_e32 v236, 6, v233
	v_bfe_u32 v233, v204, 4, 2
	v_lshl_add_u32 v236, v233, 4, v236
	v_mov_b32_e32 v237, 0
	v_lshl_add_u64 v[236:237], v[236:237], 0, s[74:75]
	global_load_dwordx4 v[226:229], v[236:237], off
	s_waitcnt vmcnt(0)
	s_branch .LBB0_1739

.LBB0_1741:
	s_ashr_i32 s2, s49, 8
	s_add_i32 s10, s2, 4
	s_and_b32 s55, s49, 63
	s_ashr_i32 s11, s10, 31
	s_bfe_u32 s60, s49, 0x20006
	v_mov_b32_e32 v185, v204
	s_lshl_b64 s[8:9], s[10:11], 12
	s_lshl_b32 s2, s55, 6
	s_or_b32 s8, s8, s2
	v_lshlrev_b32_e32 v8, 3, v185
	s_lshl_b32 s11, s60, 7
	s_lshl_b32 s2, s60, 8
	v_and_b32_e32 v158, 0x78, v8
	v_ashrrev_i32_e32 v168, 4, v185
	s_add_u32 s12, s16, s2
	s_addc_u32 s13, s17, 0
	v_lshlrev_b32_e32 v8, 1, v158
	v_ashrrev_i32_e32 v169, 31, v168
	v_lshl_add_u64 v[10:11], s[12:13], 0, v[8:9]
	v_lshl_add_u64 v[36:37], s[8:9], 0, v[168:169]
	v_add_u32_e32 v164, 32, v168
	v_mad_u64_u32 v[38:39], s[12:13], v36, s0, v[10:11]
	v_ashrrev_i32_e32 v165, 31, v164
	v_mad_i32_i24 v39, v37, s0, v39
	v_lshl_add_u64 v[36:37], s[8:9], 0, v[164:165]
	v_and_b32_e32 v131, 15, v185
	v_mad_u64_u32 v[10:11], s[12:13], v36, s0, v[10:11]
	v_mad_i32_i24 v11, v37, s0, v11
	v_or_b32_e32 v124, s8, v131
	v_mov_b64_e32 v[36:37], s[16:17]
	v_mad_u64_u32 v[134:135], s[12:13], v124, s0, v[36:37]
	v_or_b32_e32 v129, 16, v131
	v_mad_i32_i24 v135, s9, v174, v135
	v_and_b32_e32 v116, 48, v185
	v_mov_b32_e32 v117, v9
	v_or_b32_e32 v130, s8, v129
	global_load_dword v239, v[38:39], off
	v_mov_b32_e32 v96, v188
	v_mov_b32_e32 v97, v189
	v_mov_b32_e32 v98, v190
	v_mov_b32_e32 v99, v191
	global_load_dword v239, v[38:39], off offset:1024
	v_mov_b32_e32 v104, v192
	v_mov_b32_e32 v105, v193
	v_mov_b32_e32 v106, v194
	v_mov_b32_e32 v107, v195
	global_load_dword v239, v[10:11], off
	v_mov_b32_e32 v60, v196
	v_mov_b32_e32 v61, v197
	v_mov_b32_e32 v62, v198
	v_mov_b32_e32 v63, v199
	global_load_dword v239, v[10:11], off offset:1024
	v_mov_b32_e32 v100, v200
	v_mov_b32_e32 v101, v201
	v_mov_b32_e32 v102, v202
	v_mov_b32_e32 v103, v203
	v_lshl_add_u64 v[10:11], v[134:135], 0, v[116:117]
	v_mad_u64_u32 v[136:137], s[12:13], v130, s0, v[36:37]
	v_or_b32_e32 v177, 32, v131
	v_add_co_u32_e32 v10, vcc, s20, v10
	v_mad_i32_i24 v137, s9, v174, v137
	v_or_b32_e32 v128, s8, v177
	v_addc_co_u32_e32 v11, vcc, 0, v11, vcc
	v_lshl_add_u64 v[38:39], v[136:137], 0, v[116:117]
	v_mad_u64_u32 v[138:139], s[12:13], v128, s0, v[36:37]
	v_add_co_u32_e32 v38, vcc, s20, v38
	v_mad_i32_i24 v139, s9, v174, v139
	s_nop 0
	v_addc_co_u32_e32 v39, vcc, 0, v39, vcc
	global_load_dword v239, v[10:11], off offset:2048
	v_mov_b32_e32 v56, v206
	v_mov_b32_e32 v57, v207
	v_mov_b32_e32 v58, v208
	v_mov_b32_e32 v59, v209
	global_load_dword v239, v[38:39], off offset:2048
	v_mov_b32_e32 v52, v210
	v_mov_b32_e32 v53, v211
	v_mov_b32_e32 v54, v212
	v_mov_b32_e32 v55, v213
	v_lshl_add_u64 v[10:11], v[138:139], 0, v[116:117]
	v_add_co_u32_e32 v38, vcc, s20, v10
	v_ashrrev_i32_e32 v66, 6, v185
	s_nop 0
	v_addc_co_u32_e32 v39, vcc, 0, v11, vcc
	v_or_b32_e32 v11, 48, v131
	v_or_b32_e32 v10, s8, v11
	v_mad_u64_u32 v[140:141], s[12:13], v10, s0, v[36:37]
	v_mad_i32_i24 v141, s9, v174, v141
	v_lshl_add_u64 v[36:37], v[140:141], 0, v[116:117]
	v_add_co_u32_e32 v36, vcc, s20, v36
	v_lshlrev_b32_e32 v122, 4, v66
	s_nop 0
	v_addc_co_u32_e32 v37, vcc, 0, v37, vcc
	global_load_dword v239, v[38:39], off offset:2048
	v_mov_b32_e32 v44, v214
	v_mov_b32_e32 v45, v215
	v_mov_b32_e32 v46, v216
	v_mov_b32_e32 v47, v217
	s_nop 0
	global_load_dword v239, v[36:37], off offset:2048
	v_mov_b32_e32 v36, v218
	v_mov_b32_e32 v37, v219
	v_mov_b32_e32 v38, v220
	v_mov_b32_e32 v39, v221
	v_or_b32_e32 v40, s11, v131
	v_and_b32_e32 v133, 63, v185
	v_add_u32_e32 v48, v40, v122
	v_and_b32_e32 v40, 16, v185
	v_mov_b32_e32 v41, v9
	v_mov_b32_e32 v125, s9
	v_lshl_add_u64 v[50:51], s[18:19], 0, v[40:41]
	v_cmp_lt_u32_e32 vcc, 31, v133
	v_cmp_gt_u32_e64 s[8:9], 32, v133
	v_mov_b32_e32 v40, 0
	v_ashrrev_i32_e32 v49, 31, v48
	v_mov_b32_e32 v108, 0
	v_mov_b32_e32 v109, 0
	v_mov_b32_e32 v110, 0
	v_mov_b32_e32 v111, 0
	s_and_saveexec_b64 s[12:13], s[8:9]
	s_cbranch_execz .LBB0_1743
	v_lshlrev_b64 v[42:43], 5, v[48:49]
	v_lshl_add_u64 v[42:43], v[50:51], 0, v[42:43]
	global_load_dword v239, v[42:43], off
	v_mov_b32_e32 v108, v222
	v_mov_b32_e32 v109, v223
	v_mov_b32_e32 v110, v224
	v_mov_b32_e32 v111, v225

.LBB0_1769:
	s_or_b64 exec, exec, s[8:9]
	v_sub_u32_e32 v53, 0, v179
	v_sub_u32_e32 v54, 0, v202
	v_add_f32_e32 v52, v52, v40
	v_add_u32_e32 v53, v176, v53
	v_sub_u32_e32 v55, 0, v203
	ds_write_b32 v53, v52 offset:32256
	v_add_f32_e32 v51, v51, v40
	v_add_u32_e32 v52, v176, v54
	v_sub_u32_e32 v56, 0, v206
	ds_write_b32 v52, v51 offset:32256
	v_add_f32_e32 v50, v50, v40
	v_add_u32_e32 v51, v176, v55
	v_sub_u32_e32 v57, 0, v207
	ds_write_b32 v51, v50 offset:32256
	v_add_f32_e32 v49, v49, v40
	v_add_u32_e32 v50, v176, v56
	v_sub_u32_e32 v58, 0, v208
	ds_write_b32 v50, v49 offset:32256
	v_add_f32_e32 v48, v48, v40
	v_add_u32_e32 v49, v176, v57
	v_sub_u32_e32 v59, 0, v209
	ds_write_b32 v49, v48 offset:32256
	v_add_f32_e32 v47, v47, v40
	v_add_u32_e32 v48, v176, v58
	v_sub_u32_e32 v127, 0, v210
	ds_write_b32 v48, v47 offset:32256
	v_add_f32_e32 v46, v46, v40
	v_add_u32_e32 v47, v176, v59
	v_sub_u32_e32 v179, 0, v211
	ds_write_b32 v47, v46 offset:32256
	v_add_f32_e32 v45, v45, v40
	v_add_u32_e32 v46, v176, v127
	v_sub_u32_e32 v180, 0, v212
	ds_write_b32 v46, v45 offset:32256
	v_add_f32_e32 v44, v44, v40
	v_add_u32_e32 v45, v176, v179
	v_sub_u32_e32 v181, 0, v213
	ds_write_b32 v45, v44 offset:32256
	v_add_f32_e32 v43, v43, v40
	v_add_u32_e32 v44, v176, v180
	v_sub_u32_e32 v182, 0, v214
	ds_write_b32 v44, v43 offset:32256
	v_add_f32_e32 v42, v42, v40
	v_add_u32_e32 v43, v176, v181
	v_sub_u32_e32 v202, 0, v215
	ds_write_b32 v43, v42 offset:32256
	v_add_f32_e32 v41, v41, v40
	v_add_u32_e32 v42, v176, v182
	v_sub_u32_e32 v203, 0, v216
	ds_write_b32 v42, v41 offset:32256
	v_add_f32_e32 v39, v39, v40
	v_add_u32_e32 v41, v176, v202
	v_sub_u32_e32 v206, 0, v217
	ds_write_b32 v41, v39 offset:32256
	v_add_f32_e32 v38, v38, v40
	v_add_u32_e32 v39, v176, v203
	v_sub_u32_e32 v207, 0, v218
	ds_write_b32 v39, v38 offset:32256
	v_add_f32_e32 v37, v37, v40
	v_add_u32_e32 v38, v176, v206
	ds_write_b32 v38, v37 offset:32256
	v_add_f32_e32 v36, v36, v40
	v_add_u32_e32 v37, v176, v207
	ds_write_b32 v37, v36 offset:32256
	s_waitcnt lgkmcnt(0)
	s_barrier
	ds_read_b128 v[36:39], v186
	ds_read_b128 v[40:43], v184 offset:15872
	ds_read_b128 v[44:47], v184 offset:15888
	ds_read_b128 v[48:51], v186 offset:16
	s_waitcnt lgkmcnt(2)
	v_sub_f32_e32 v53, v40, v36
	v_mul_f32_e32 v53, 0x3fb8aa3b, v53
	v_sub_f32_e32 v55, v41, v37
	v_sub_f32_e32 v52, v36, v40
	v_exp_f32_e32 v54, v53
	v_sub_f32_e32 v53, v37, v41
	v_mul_f32_e32 v55, 0x3fb8aa3b, v55
	v_mul_f32_e32 v36, 0x3fb8aa3b, v36
	v_mul_f32_e32 v37, 0x3fb8aa3b, v37
	v_sub_f32_e32 v57, v42, v38
	v_exp_f32_e32 v55, v55
	v_exp_f32_e32 v36, v36
	v_exp_f32_e32 v37, v37
	v_mul_f32_e32 v57, 0x3fb8aa3b, v57
	v_sub_f32_e32 v59, v43, v39
	v_sub_f32_e32 v56, v38, v42
	v_exp_f32_e32 v58, v57
	v_mul_f32_e32 v38, 0x3fb8aa3b, v38
	v_sub_f32_e32 v57, v39, v43
	v_mul_f32_e32 v59, 0x3fb8aa3b, v59
	v_mul_f32_e32 v39, 0x3fb8aa3b, v39
	v_exp_f32_e32 v38, v38
	v_exp_f32_e32 v59, v59
	v_exp_f32_e32 v39, v39
	v_pk_mul_f32 v[54:55], v[54:55], v[156:157]
	v_pk_mul_f32 v[156:157], v[158:159], v[36:37]
	s_waitcnt lgkmcnt(0)
	v_sub_f32_e32 v37, v44, v48
	v_mul_f32_e32 v37, 0x3fb8aa3b, v37
	v_pk_mul_f32 v[58:59], v[58:59], v[154:155]
	v_pk_mul_f32 v[154:155], v[162:163], v[38:39]
	v_sub_f32_e32 v36, v48, v44
	v_exp_f32_e32 v38, v37
	v_sub_f32_e32 v37, v49, v45
	v_mul_f32_e32 v52, 0x3fb8aa3b, v52
	v_mul_f32_e32 v53, 0x3fb8aa3b, v53
	v_mul_f32_e32 v36, 0x3fb8aa3b, v36
	v_mul_f32_e32 v37, 0x3fb8aa3b, v37
	v_exp_f32_e32 v52, v52
	v_exp_f32_e32 v53, v53
	v_exp_f32_e32 v36, v36
	v_exp_f32_e32 v37, v37
	v_sub_f32_e32 v39, v45, v49
	v_mul_f32_e32 v39, 0x3fb8aa3b, v39
	v_exp_f32_e32 v39, v39
	v_pk_mul_f32 v[52:53], v[158:159], v[52:53]
	v_pk_mul_f32 v[158:159], v[160:161], v[36:37]
	v_sub_f32_e32 v37, v46, v50
	v_mul_f32_e32 v37, 0x3fb8aa3b, v37
	v_pk_mul_f32 v[152:153], v[38:39], v[152:153]
	v_mul_f32_e32 v36, 0x3fb8aa3b, v49
	v_exp_f32_e32 v38, v37
	v_mul_f32_e32 v37, 0x3fb8aa3b, v50
	v_exp_f32_e32 v49, v36
	v_sub_f32_e32 v36, v50, v46
	v_exp_f32_e32 v50, v37
	v_sub_f32_e32 v37, v51, v47
	v_mul_f32_e32 v56, 0x3fb8aa3b, v56
	v_mul_f32_e32 v57, 0x3fb8aa3b, v57
	v_mul_f32_e32 v48, 0x3fb8aa3b, v48
	v_mul_f32_e32 v36, 0x3fb8aa3b, v36
	v_mul_f32_e32 v37, 0x3fb8aa3b, v37
	v_sub_f32_e32 v39, v47, v51
	v_exp_f32_e32 v56, v56
	v_exp_f32_e32 v57, v57
	v_exp_f32_e32 v48, v48
	v_exp_f32_e32 v36, v36
	v_exp_f32_e32 v37, v37
	v_mul_f32_e32 v39, 0x3fb8aa3b, v39
	v_exp_f32_e32 v39, v39
	v_mul_f32_e32 v51, 0x3fb8aa3b, v51
	v_exp_f32_e32 v51, v51
	v_pk_mul_f32 v[56:57], v[162:163], v[56:57]
	v_pk_mul_f32 v[48:49], v[160:161], v[48:49]
	v_pk_mul_f32 v[160:161], v[166:167], v[36:37]
	v_pk_mul_f32 v[150:151], v[38:39], v[150:151]
	v_cvt_pk_bf16_f32 v36, v52, v53
	v_cvt_pk_bf16_f32 v37, v56, v57
	v_cvt_pk_bf16_f32 v38, v158, v159
	v_cvt_pk_bf16_f32 v39, v160, v161
	v_pk_mul_f32 v[50:51], v[166:167], v[50:51]
	ds_write_b128 v183, v[36:39] offset:32768
	v_cvt_pk_bf16_f32 v36, v54, v55
	v_cvt_pk_bf16_f32 v37, v58, v59
	v_cvt_pk_bf16_f32 v38, v152, v153
	v_cvt_pk_bf16_f32 v39, v150, v151
	ds_write_b128 v183, v[36:39] offset:50176
	v_cvt_pk_bf16_f32 v36, v156, v157
	v_cvt_pk_bf16_f32 v37, v154, v155
	v_cvt_pk_bf16_f32 v38, v48, v49
	v_cvt_pk_bf16_f32 v39, v50, v51
	ds_write_b128 v8, v[36:39]
	ds_read_b128 v[36:39], v189
	ds_read_b128 v[48:51], v189 offset:16
	s_waitcnt lgkmcnt(1)
	v_sub_f32_e32 v52, v36, v40
	v_sub_f32_e32 v40, v40, v36
	v_sub_f32_e32 v53, v37, v41
	v_sub_f32_e32 v41, v41, v37
	v_mul_f32_e32 v36, 0x3fb8aa3b, v36
	v_mul_f32_e32 v37, 0x3fb8aa3b, v37
	v_exp_f32_e32 v36, v36
	v_exp_f32_e32 v37, v37
	v_sub_f32_e32 v54, v38, v42
	v_sub_f32_e32 v42, v42, v38
	v_mul_f32_e32 v38, 0x3fb8aa3b, v38
	v_sub_f32_e32 v55, v39, v43
	v_sub_f32_e32 v43, v43, v39
	v_mul_f32_e32 v39, 0x3fb8aa3b, v39
	v_exp_f32_e32 v38, v38
	v_exp_f32_e32 v39, v39
	v_pk_mul_f32 v[56:57], v[164:165], v[36:37]
	s_waitcnt lgkmcnt(0)
	v_sub_f32_e32 v37, v44, v48
	v_mul_f32_e32 v37, 0x3fb8aa3b, v37
	v_pk_mul_f32 v[58:59], v[170:171], v[38:39]
	v_sub_f32_e32 v36, v48, v44
	v_exp_f32_e32 v38, v37
	v_sub_f32_e32 v37, v49, v45
	v_mul_f32_e32 v42, 0x3fb8aa3b, v42
	v_mul_f32_e32 v43, 0x3fb8aa3b, v43
	v_mul_f32_e32 v36, 0x3fb8aa3b, v36
	v_mul_f32_e32 v37, 0x3fb8aa3b, v37
	v_exp_f32_e32 v42, v42
	v_exp_f32_e32 v43, v43
	v_exp_f32_e32 v36, v36
	v_exp_f32_e32 v37, v37
	v_sub_f32_e32 v39, v45, v49
	v_mul_f32_e32 v39, 0x3fb8aa3b, v39
	v_exp_f32_e32 v39, v39
	v_pk_mul_f32 v[42:43], v[42:43], v[146:147]
	v_pk_mul_f32 v[146:147], v[168:169], v[36:37]
	v_sub_f32_e32 v37, v46, v50
	v_mul_f32_e32 v37, 0x3fb8aa3b, v37
	v_pk_mul_f32 v[144:145], v[38:39], v[144:145]
	v_mul_f32_e32 v36, 0x3fb8aa3b, v49
	v_exp_f32_e32 v38, v37
	v_mul_f32_e32 v37, 0x3fb8aa3b, v50
	v_exp_f32_e32 v45, v36
	v_sub_f32_e32 v36, v50, v46
	v_exp_f32_e32 v46, v37
	v_sub_f32_e32 v37, v51, v47
	v_mul_f32_e32 v52, 0x3fb8aa3b, v52
	v_mul_f32_e32 v53, 0x3fb8aa3b, v53
	v_mul_f32_e32 v54, 0x3fb8aa3b, v54
	v_mul_f32_e32 v55, 0x3fb8aa3b, v55
	v_mul_f32_e32 v36, 0x3fb8aa3b, v36
	v_mul_f32_e32 v37, 0x3fb8aa3b, v37
	v_sub_f32_e32 v39, v47, v51
	v_exp_f32_e32 v52, v52
	v_mul_f32_e32 v40, 0x3fb8aa3b, v40
	v_exp_f32_e32 v53, v53
	v_mul_f32_e32 v41, 0x3fb8aa3b, v41
	v_exp_f32_e32 v54, v54
	v_exp_f32_e32 v55, v55
	v_exp_f32_e32 v36, v36
	v_exp_f32_e32 v37, v37
	v_mul_f32_e32 v39, 0x3fb8aa3b, v39
	v_exp_f32_e32 v40, v40
	v_exp_f32_e32 v41, v41
	v_mul_f32_e32 v44, 0x3fb8aa3b, v48
	v_exp_f32_e32 v39, v39
	v_mul_f32_e32 v47, 0x3fb8aa3b, v51
	v_exp_f32_e32 v44, v44
	v_exp_f32_e32 v47, v47
	v_pk_mul_f32 v[52:53], v[164:165], v[52:53]
	v_pk_mul_f32 v[54:55], v[170:171], v[54:55]
	v_pk_mul_f32 v[48:49], v[172:173], v[36:37]
	v_pk_mul_f32 v[40:41], v[40:41], v[148:149]
	v_pk_mul_f32 v[50:51], v[38:39], v[142:143]
	v_cvt_pk_bf16_f32 v36, v52, v53
	v_cvt_pk_bf16_f32 v37, v54, v55
	v_cvt_pk_bf16_f32 v38, v146, v147
	v_cvt_pk_bf16_f32 v39, v48, v49
	v_pk_mul_f32 v[44:45], v[168:169], v[44:45]
	v_pk_mul_f32 v[46:47], v[172:173], v[46:47]
	ds_write_b128 v183, v[36:39] offset:41472
	v_cvt_pk_bf16_f32 v36, v40, v41
	v_cvt_pk_bf16_f32 v37, v42, v43
	v_cvt_pk_bf16_f32 v38, v144, v145
	v_cvt_pk_bf16_f32 v39, v50, v51
	ds_write_b128 v183, v[36:39] offset:58880
	v_cvt_pk_bf16_f32 v36, v56, v57
	v_cvt_pk_bf16_f32 v37, v58, v59
	v_cvt_pk_bf16_f32 v38, v44, v45
	v_cvt_pk_bf16_f32 v39, v46, v47
	ds_write_b128 v8, v[36:39] offset:8704
	s_waitcnt lgkmcnt(0)
	s_barrier
	ds_read_b128 v[36:39], v190 offset:50176
	ds_read_b128 v[40:43], v191 offset:32768
	ds_read_b128 v[44:47], v191 offset:32832
	ds_read_b128 v[48:51], v190 offset:50240
	s_waitcnt lgkmcnt(2)
	v_mfma_f32_16x16x32_bf16 v[36:39], v[36:39], v[40:43], 0
	ds_read_b128 v[52:55], v190 offset:54528
	ds_read_b128 v[56:59], v190 offset:54592
	v_mul_u32_u24_e32 v8, 0x90, v131
	v_add_u32_e32 v8, v188, v8
	s_waitcnt lgkmcnt(2)
	v_mfma_f32_16x16x32_bf16 v[36:39], v[48:51], v[44:47], v[36:39]
	ds_read_b128 v[48:51], v190 offset:50304
	s_waitcnt lgkmcnt(2)
	v_mfma_f32_16x16x32_bf16 v[40:43], v[52:55], v[40:43], 0
	s_waitcnt lgkmcnt(1)
	v_mfma_f32_16x16x32_bf16 v[40:43], v[56:59], v[44:47], v[40:43]
	ds_read_b128 v[44:47], v191 offset:32896
	ds_read_b128 v[52:55], v191 offset:32960
	ds_read_b128 v[56:59], v190 offset:50368
	s_waitcnt lgkmcnt(2)
	v_mfma_f32_16x16x32_bf16 v[36:39], v[48:51], v[44:47], v[36:39]
	ds_read_b128 v[48:51], v190 offset:54656
	ds_read_b128 v[142:145], v190 offset:54720
	s_waitcnt lgkmcnt(1)
	v_mfma_f32_16x16x32_bf16 v[40:43], v[48:51], v[44:47], v[40:43]
	v_or_b32_e32 v45, 1, v192
	v_cmp_le_i32_e32 vcc, v187, v45
	v_mul_u32_u24_e32 v44, 0x220, v194
	v_mfma_f32_16x16x32_bf16 v[36:39], v[56:59], v[52:55], v[36:39]
	v_add_u32_e32 v127, v185, v44
	s_waitcnt lgkmcnt(0)
	v_mfma_f32_16x16x32_bf16 v[40:43], v[142:145], v[52:55], v[40:43]
	s_nop 4
	v_cndmask_b32_e32 v37, 0, v37, vcc
	v_cmp_le_i32_e32 vcc, v187, v195
	v_cndmask_b32_e64 v36, v36, 0, s[14:15]
	v_cvt_pk_bf16_f32 v36, v36, v37
	v_cndmask_b32_e32 v38, 0, v38, vcc
	v_cmp_le_i32_e32 vcc, v187, v196
	s_nop 1
	v_cndmask_b32_e32 v39, 0, v39, vcc
	v_cmp_le_i32_e32 vcc, v187, v197
	v_cvt_pk_bf16_f32 v37, v38, v39
	s_nop 0
	v_cndmask_b32_e32 v38, 0, v40, vcc
	v_cmp_le_i32_e32 vcc, v187, v198
	s_nop 1
	v_cndmask_b32_e32 v39, 0, v41, vcc
	v_cmp_le_i32_e32 vcc, v187, v200
	v_cvt_pk_bf16_f32 v38, v38, v39
	s_nop 0
	v_cndmask_b32_e32 v40, 0, v42, vcc
	v_cmp_le_i32_e32 vcc, v187, v201
	s_nop 1
	v_cndmask_b32_e32 v41, 0, v43, vcc
	v_cvt_pk_bf16_f32 v39, v40, v41
	ds_write2_b64 v193, v[36:37], v[38:39] offset1:4
	s_waitcnt lgkmcnt(0)
	s_barrier
	ds_read_b64_tr_b16 v[38:39], v127 offset:2176
	ds_read_b64_tr_b16 v[36:37], v127
	ds_read_b64_tr_b16 v[42:43], v127 offset:2184
	ds_read_b64_tr_b16 v[40:41], v127 offset:8
	ds_read_b128 v[44:47], v8
	ds_read_b128 v[48:51], v8 offset:64
	s_waitcnt lgkmcnt(1)
	v_mfma_f32_16x16x32_bf16 v[52:55], v[36:39], v[44:47], v[88:91]
	ds_read_b128 v[56:59], v8 offset:2304
	s_nop 1
	ds_read_b128 v[88:91], v8 offset:2368
	v_mfma_f32_16x16x32_bf16 v[44:47], v[40:43], v[44:47], v[92:95]
	s_waitcnt lgkmcnt(1)
	v_mfma_f32_16x16x32_bf16 v[80:83], v[36:39], v[56:59], v[80:83]
	v_mfma_f32_16x16x32_bf16 v[56:59], v[40:43], v[56:59], v[84:87]
	s_nop 2
	ds_read_b128 v[84:87], v8 offset:4608
	ds_read_b128 v[92:95], v8 offset:4672
	s_waitcnt lgkmcnt(1)
	v_mfma_f32_16x16x32_bf16 v[68:71], v[36:39], v[84:87], v[68:71]
	v_mfma_f32_16x16x32_bf16 v[76:79], v[40:43], v[84:87], v[76:79]
	ds_read_b128 v[84:87], v8 offset:6912
	ds_read_b128 v[142:145], v8 offset:6976
	v_mul_u32_u24_e32 v8, 0x110, v131
	v_add_u32_e32 v8, v199, v8
	s_waitcnt lgkmcnt(1)
	v_mfma_f32_16x16x32_bf16 v[36:39], v[36:39], v[84:87], v[64:67]
	s_nop 2
	ds_read_b64_tr_b16 v[64:65], v127 offset:17408
	ds_read_b64_tr_b16 v[66:67], v127 offset:19584
	v_mfma_f32_16x16x32_bf16 v[40:43], v[40:43], v[84:87], v[60:63]
	s_nop 2
	ds_read_b64_tr_b16 v[62:63], v127 offset:19592
	ds_read_b64_tr_b16 v[60:61], v127 offset:17416
	s_waitcnt lgkmcnt(2)
	v_mfma_f32_16x16x32_bf16 v[52:55], v[64:67], v[48:51], v[52:55]
	s_waitcnt lgkmcnt(0)
	v_mfma_f32_16x16x32_bf16 v[44:47], v[60:63], v[48:51], v[44:47]
	v_mfma_f32_16x16x32_bf16 v[48:51], v[64:67], v[88:91], v[80:83]
	v_mfma_f32_16x16x32_bf16 v[56:59], v[60:63], v[88:91], v[56:59]
	v_mfma_f32_16x16x32_bf16 v[68:71], v[64:67], v[92:95], v[68:71]
	v_mfma_f32_16x16x32_bf16 v[76:79], v[60:63], v[92:95], v[76:79]
	v_mfma_f32_16x16x32_bf16 v[36:39], v[64:67], v[142:145], v[36:39]
	v_mfma_f32_16x16x32_bf16 v[40:43], v[60:63], v[142:145], v[40:43]
	ds_read_b128 v[60:63], v8
	ds_read_b128 v[64:67], v8 offset:64
	s_waitcnt vmcnt(7) lgkmcnt(1)
	v_mfma_f32_16x16x32_bf16 v[52:55], v[116:119], v[60:63], v[52:55]
	s_waitcnt vmcnt(3)
	v_mfma_f32_16x16x32_bf16 v[44:47], v[120:123], v[60:63], v[44:47]
	ds_read_b128 v[60:63], v8 offset:4352
	ds_read_b128 v[80:83], v8 offset:4416
	s_waitcnt lgkmcnt(1)
	v_mfma_f32_16x16x32_bf16 v[48:51], v[116:119], v[60:63], v[48:51]
	v_mfma_f32_16x16x32_bf16 v[56:59], v[120:123], v[60:63], v[56:59]
	ds_read_b128 v[60:63], v8 offset:8704
	ds_read_b128 v[84:87], v8 offset:8768
	s_waitcnt lgkmcnt(1)
	v_mfma_f32_16x16x32_bf16 v[68:71], v[116:119], v[60:63], v[68:71]
	v_mfma_f32_16x16x32_bf16 v[60:63], v[120:123], v[60:63], v[76:79]
	s_nop 2
	ds_read_b128 v[76:79], v8 offset:13056
	ds_read_b128 v[88:91], v8 offset:13120
	s_waitcnt lgkmcnt(1)
	v_mfma_f32_16x16x32_bf16 v[36:39], v[116:119], v[76:79], v[36:39]
	v_mfma_f32_16x16x32_bf16 v[40:43], v[120:123], v[76:79], v[40:43]
	v_mfma_f32_16x16x32_bf16 v[52:55], v[108:111], v[64:67], v[52:55]
	s_waitcnt vmcnt(2)
	v_mfma_f32_16x16x32_bf16 v[44:47], v[112:115], v[64:67], v[44:47]
	v_mfma_f32_16x16x32_bf16 v[48:51], v[108:111], v[80:83], v[48:51]
	v_mfma_f32_16x16x32_bf16 v[56:59], v[112:115], v[80:83], v[56:59]
	v_mfma_f32_16x16x32_bf16 v[64:67], v[108:111], v[84:87], v[68:71]
	v_mfma_f32_16x16x32_bf16 v[60:63], v[112:115], v[84:87], v[60:63]
	s_waitcnt lgkmcnt(0)
	v_mfma_f32_16x16x32_bf16 v[36:39], v[108:111], v[88:91], v[36:39]
	v_mfma_f32_16x16x32_bf16 v[40:43], v[112:115], v[88:91], v[40:43]
	ds_read_b128 v[68:71], v8 offset:128
	ds_read_b128 v[76:79], v8 offset:192
	s_waitcnt lgkmcnt(1)
	v_mfma_f32_16x16x32_bf16 v[52:55], v[100:103], v[68:71], v[52:55]
	s_waitcnt vmcnt(1)
	v_mfma_f32_16x16x32_bf16 v[44:47], v[104:107], v[68:71], v[44:47]
	ds_read_b128 v[68:71], v8 offset:4480
	ds_read_b128 v[84:87], v8 offset:4544
	s_waitcnt lgkmcnt(1)
	v_mfma_f32_16x16x32_bf16 v[48:51], v[100:103], v[68:71], v[48:51]
	v_mfma_f32_16x16x32_bf16 v[56:59], v[104:107], v[68:71], v[56:59]
	ds_read_b128 v[68:71], v8 offset:8832
	ds_read_b128 v[88:91], v8 offset:8896
	s_waitcnt lgkmcnt(1)
	v_mfma_f32_16x16x32_bf16 v[92:95], v[100:103], v[68:71], v[64:67]
	v_mfma_f32_16x16x32_bf16 v[68:71], v[104:107], v[68:71], v[60:63]
	s_nop 2
	ds_read_b128 v[60:63], v8 offset:13184
	ds_read_b128 v[108:111], v8 offset:13248
	s_waitcnt lgkmcnt(1)
	v_mfma_f32_16x16x32_bf16 v[36:39], v[100:103], v[60:63], v[36:39]
	v_mfma_f32_16x16x32_bf16 v[100:103], v[104:107], v[60:63], v[40:43]
	v_mfma_f32_16x16x32_bf16 v[80:83], v[72:75], v[76:79], v[52:55]
	s_waitcnt vmcnt(0)
	v_mfma_f32_16x16x32_bf16 v[76:79], v[96:99], v[76:79], v[44:47]
	v_mfma_f32_16x16x32_bf16 v[64:67], v[72:75], v[84:87], v[48:51]
	v_mfma_f32_16x16x32_bf16 v[60:63], v[96:99], v[84:87], v[56:59]
	v_mfma_f32_16x16x32_bf16 v[52:55], v[72:75], v[88:91], v[92:95]
	v_mfma_f32_16x16x32_bf16 v[48:51], v[96:99], v[88:91], v[68:71]
	s_waitcnt lgkmcnt(0)
	v_mfma_f32_16x16x32_bf16 v[40:43], v[72:75], v[108:111], v[36:39]
	v_mfma_f32_16x16x32_bf16 v[36:39], v[96:99], v[108:111], v[100:103]
	s_cmpk_gt_i32 s47, 0x3ff
	s_cbranch_scc1 .Lgca_skip
	s_ashr_i32 s61, s47, 8
	s_add_i32 s61, s61, 4
	s_lshl_b32 s61, s61, 12
	s_and_b32 s62, s47, 63
	s_lshl_b32 s62, s62, 6
	s_or_b32 s61, s61, s62
	s_bfe_u32 s62, s47, 0x20006
	s_lshl_b32 s63, s62, 7
	s_mov_b32 s66, s20
	s_mov_b32 s67, 0
	v_and_b32_e32 v230, 48, v204
	v_mov_b32_e32 v231, 0
	v_and_b32_e32 v232, 15, v204
	s_lshl_b32 s78, s62, 8
	s_add_u32 s78, s16, s78
	s_addc_u32 s79, s17, 0
	v_lshlrev_b32_e32 v236, 4, v232
	v_mov_b32_e32 v237, 0
	v_lshl_add_u64 v[234:235], v[236:237], 0, s[78:79]
	v_lshrrev_b32_e32 v233, 4, v204
	v_or_b32_e32 v233, s61, v233
	v_mad_u64_u32 v[236:237], s[64:65], v233, s0, v[234:235]
	global_load_dwordx4 v[188:191], v[236:237], off
	global_load_dwordx4 v[192:195], v[236:237], off offset:1024
	v_or_b32_e32 v233, 32, v233
	v_mad_u64_u32 v[236:237], s[64:65], v233, s0, v[234:235]
	global_load_dwordx4 v[196:199], v[236:237], off
	global_load_dwordx4 v[200:203], v[236:237], off offset:1024
	v_mov_b64_e32 v[234:235], s[16:17]
	v_or_b32_e32 v233, s61, v232
	v_mad_u64_u32 v[236:237], s[64:65], v233, s0, v[234:235]
	v_lshl_add_u64 v[236:237], v[236:237], 0, v[230:231]
	v_lshl_add_u64 v[236:237], v[236:237], 0, s[66:67]
	global_load_dwordx4 v[206:209], v[236:237], off offset:2048
	v_or_b32_e32 v233, 16, v232
	v_or_b32_e32 v233, s61, v233
	v_mad_u64_u32 v[236:237], s[64:65], v233, s0, v[234:235]
	v_lshl_add_u64 v[236:237], v[236:237], 0, v[230:231]
	v_lshl_add_u64 v[236:237], v[236:237], 0, s[66:67]
	global_load_dwordx4 v[210:213], v[236:237], off offset:2048
	v_or_b32_e32 v233, 32, v232
	v_or_b32_e32 v233, s61, v233
	v_mad_u64_u32 v[236:237], s[64:65], v233, s0, v[234:235]
	v_lshl_add_u64 v[236:237], v[236:237], 0, v[230:231]
	v_lshl_add_u64 v[236:237], v[236:237], 0, s[66:67]
	global_load_dwordx4 v[214:217], v[236:237], off offset:2048
	v_or_b32_e32 v233, 48, v232
	v_or_b32_e32 v233, s61, v233
	v_mad_u64_u32 v[236:237], s[64:65], v233, s0, v[234:235]
	v_lshl_add_u64 v[236:237], v[236:237], 0, v[230:231]
	v_lshl_add_u64 v[236:237], v[236:237], 0, s[66:67]
	global_load_dwordx4 v[218:221], v[236:237], off offset:2048
	v_lshrrev_b32_e32 v233, 6, v204
	v_lshlrev_b32_e32 v233, 4, v233
	v_or_b32_e32 v236, s63, v232
	v_add_u32_e32 v236, v236, v233
	v_lshlrev_b32_e32 v236, 5, v236
	v_and_b32_e32 v233, 16, v204
	v_add_u32_e32 v236, v236, v233
	v_mov_b32_e32 v237, 0
	v_lshl_add_u64 v[236:237], v[236:237], 0, s[18:19]
	v_mov_b32_e32 v222, 0
	v_mov_b32_e32 v223, 0
	v_mov_b32_e32 v224, 0
	v_mov_b32_e32 v225, 0
	v_and_b32_e32 v233, 63, v204
	v_cmp_gt_u32_e32 vcc, 32, v233
	s_and_saveexec_b64 s[70:71], vcc
	global_load_dwordx4 v[222:225], v[236:237], off
	s_or_b64 exec, exec, s[70:71]
	s_lshl_b32 s63, s63, 2
	s_add_u32 s74, s24, s63
	s_addc_u32 s75, s25, 0
	v_lshrrev_b32_e32 v233, 6, v204
	v_lshlrev_b32_e32 v236, 6, v233
	v_bfe_u32 v233, v204, 4, 2
	v_lshl_add_u32 v236, v233, 4, v236
	v_mov_b32_e32 v237, 0
	v_lshl_add_u64 v[236:237], v[236:237], 0, s[74:75]
	global_load_dwordx4 v[226:229], v[236:237], off

.LBB0_1780:
	s_ashr_i32 s2, s47, 8
	s_add_i32 s10, s2, 4
	s_and_b32 s55, s47, 63
	s_ashr_i32 s11, s10, 31
	s_bfe_u32 s49, s47, 0x20006
	v_mov_b32_e32 v187, v204
	s_lshl_b64 s[8:9], s[10:11], 12
	s_lshl_b32 s2, s55, 6
	s_or_b32 s8, s8, s2
	v_lshlrev_b32_e32 v8, 3, v187
	s_lshl_b32 s11, s49, 7
	s_lshl_b32 s2, s49, 8
	v_and_b32_e32 v158, 0x78, v8
	v_ashrrev_i32_e32 v168, 4, v187
	s_add_u32 s12, s16, s2
	s_addc_u32 s13, s17, 0
	v_lshlrev_b32_e32 v8, 1, v158
	v_ashrrev_i32_e32 v169, 31, v168
	v_lshl_add_u64 v[10:11], s[12:13], 0, v[8:9]
	v_lshl_add_u64 v[36:37], s[8:9], 0, v[168:169]
	v_add_u32_e32 v164, 32, v168
	v_mad_u64_u32 v[38:39], s[12:13], v36, s0, v[10:11]
	v_ashrrev_i32_e32 v165, 31, v164
	v_mad_i32_i24 v39, v37, s0, v39
	v_lshl_add_u64 v[36:37], s[8:9], 0, v[164:165]
	v_mad_u64_u32 v[10:11], s[12:13], v36, s0, v[10:11]
	v_and_b32_e32 v131, 15, v187
	v_mad_i32_i24 v11, v37, s0, v11
	global_load_dword v239, v[38:39], off
	v_mov_b32_e32 v96, v188
	v_mov_b32_e32 v97, v189
	v_mov_b32_e32 v98, v190
	v_mov_b32_e32 v99, v191
	global_load_dword v239, v[38:39], off offset:1024
	v_mov_b32_e32 v104, v192
	v_mov_b32_e32 v105, v193
	v_mov_b32_e32 v106, v194
	v_mov_b32_e32 v107, v195
	global_load_dword v239, v[10:11], off
	v_mov_b32_e32 v60, v196
	v_mov_b32_e32 v61, v197
	v_mov_b32_e32 v62, v198
	v_mov_b32_e32 v63, v199
	global_load_dword v239, v[10:11], off offset:1024
	v_mov_b32_e32 v100, v200
	v_mov_b32_e32 v101, v201
	v_mov_b32_e32 v102, v202
	v_mov_b32_e32 v103, v203
	v_or_b32_e32 v10, s8, v131
	v_mov_b64_e32 v[36:37], s[16:17]
	v_mad_u64_u32 v[134:135], s[12:13], v10, s0, v[36:37]
	v_or_b32_e32 v129, 16, v131
	v_mad_i32_i24 v135, s9, v174, v135
	v_and_b32_e32 v116, 48, v187
	v_mov_b32_e32 v117, v9
	v_or_b32_e32 v130, s8, v129
	v_lshl_add_u64 v[38:39], v[134:135], 0, v[116:117]
	v_mad_u64_u32 v[136:137], s[12:13], v130, s0, v[36:37]
	v_or_b32_e32 v177, 32, v131
	v_add_co_u32_e32 v38, vcc, s20, v38
	v_mad_i32_i24 v137, s9, v174, v137
	v_or_b32_e32 v128, s8, v177
	v_addc_co_u32_e32 v39, vcc, 0, v39, vcc
	v_lshl_add_u64 v[40:41], v[136:137], 0, v[116:117]
	v_mad_u64_u32 v[138:139], s[12:13], v128, s0, v[36:37]
	v_or_b32_e32 v125, 48, v131
	v_add_co_u32_e32 v40, vcc, s20, v40
	v_mad_i32_i24 v139, s9, v174, v139
	v_or_b32_e32 v124, s8, v125
	v_addc_co_u32_e32 v41, vcc, 0, v41, vcc
	global_load_dword v239, v[38:39], off offset:2048
	v_mov_b32_e32 v56, v206
	v_mov_b32_e32 v57, v207
	v_mov_b32_e32 v58, v208
	v_mov_b32_e32 v59, v209
	global_load_dword v239, v[40:41], off offset:2048
	v_mov_b32_e32 v52, v210
	v_mov_b32_e32 v53, v211
	v_mov_b32_e32 v54, v212
	v_mov_b32_e32 v55, v213
	v_lshl_add_u64 v[38:39], v[138:139], 0, v[116:117]
	v_mad_u64_u32 v[140:141], s[12:13], v124, s0, v[36:37]
	v_add_co_u32_e32 v38, vcc, s20, v38
	v_mad_i32_i24 v141, s9, v174, v141
	s_nop 0
	v_addc_co_u32_e32 v39, vcc, 0, v39, vcc
	v_lshl_add_u64 v[36:37], v[140:141], 0, v[116:117]
	v_add_co_u32_e32 v36, vcc, s20, v36
	v_ashrrev_i32_e32 v66, 6, v187
	s_nop 0
	v_addc_co_u32_e32 v37, vcc, 0, v37, vcc
	global_load_dword v239, v[38:39], off offset:2048
	v_mov_b32_e32 v44, v214
	v_mov_b32_e32 v45, v215
	v_mov_b32_e32 v46, v216
	v_mov_b32_e32 v47, v217
	s_nop 0
	global_load_dword v239, v[36:37], off offset:2048
	v_mov_b32_e32 v36, v218
	v_mov_b32_e32 v37, v219
	v_mov_b32_e32 v38, v220
	v_mov_b32_e32 v39, v221
	v_lshlrev_b32_e32 v122, 4, v66
	v_or_b32_e32 v40, s11, v131
	v_and_b32_e32 v133, 63, v187
	v_add_u32_e32 v48, v40, v122
	v_and_b32_e32 v40, 16, v187
	v_mov_b32_e32 v41, v9
	v_mov_b32_e32 v11, s9
	v_lshl_add_u64 v[50:51], s[18:19], 0, v[40:41]
	v_cmp_lt_u32_e32 vcc, 31, v133
	v_cmp_gt_u32_e64 s[8:9], 32, v133
	v_mov_b32_e32 v40, 0
	v_ashrrev_i32_e32 v49, 31, v48
	v_mov_b32_e32 v108, 0
	v_mov_b32_e32 v109, 0
	v_mov_b32_e32 v110, 0
	v_mov_b32_e32 v111, 0
	s_and_saveexec_b64 s[12:13], s[8:9]
	s_cbranch_execz .LBB0_1782
	v_lshlrev_b64 v[42:43], 5, v[48:49]
	v_lshl_add_u64 v[42:43], v[50:51], 0, v[42:43]
	global_load_dword v239, v[42:43], off
	v_mov_b32_e32 v108, v222
	v_mov_b32_e32 v109, v223
	v_mov_b32_e32 v110, v224
	v_mov_b32_e32 v111, v225

.LBB0_1808:
	s_or_b64 exec, exec, s[8:9]
	v_sub_u32_e32 v53, 0, v181
	v_sub_u32_e32 v54, 0, v206
	v_add_f32_e32 v52, v52, v40
	v_add_u32_e32 v53, v180, v53
	v_sub_u32_e32 v55, 0, v207
	ds_write_b32 v53, v52 offset:32256
	v_add_f32_e32 v51, v51, v40
	v_add_u32_e32 v52, v180, v54
	v_sub_u32_e32 v56, 0, v208
	ds_write_b32 v52, v51 offset:32256
	v_add_f32_e32 v50, v50, v40
	v_add_u32_e32 v51, v180, v55
	v_sub_u32_e32 v57, 0, v209
	ds_write_b32 v51, v50 offset:32256
	v_add_f32_e32 v49, v49, v40
	v_add_u32_e32 v50, v180, v56
	v_sub_u32_e32 v58, 0, v210
	ds_write_b32 v50, v49 offset:32256
	v_add_f32_e32 v48, v48, v40
	v_add_u32_e32 v49, v180, v57
	v_sub_u32_e32 v59, 0, v211
	ds_write_b32 v49, v48 offset:32256
	v_add_f32_e32 v47, v47, v40
	v_add_u32_e32 v48, v180, v58
	v_sub_u32_e32 v127, 0, v212
	ds_write_b32 v48, v47 offset:32256
	v_add_f32_e32 v46, v46, v40
	v_add_u32_e32 v47, v180, v59
	v_sub_u32_e32 v181, 0, v213
	ds_write_b32 v47, v46 offset:32256
	v_add_f32_e32 v45, v45, v40
	v_add_u32_e32 v46, v180, v127
	v_sub_u32_e32 v182, 0, v214
	ds_write_b32 v46, v45 offset:32256
	v_add_f32_e32 v44, v44, v40
	v_add_u32_e32 v45, v180, v181
	v_sub_u32_e32 v183, 0, v215
	ds_write_b32 v45, v44 offset:32256
	v_add_f32_e32 v43, v43, v40
	v_add_u32_e32 v44, v180, v182
	v_sub_u32_e32 v184, 0, v216
	ds_write_b32 v44, v43 offset:32256
	v_add_f32_e32 v42, v42, v40
	v_add_u32_e32 v43, v180, v183
	v_sub_u32_e32 v206, 0, v217
	ds_write_b32 v43, v42 offset:32256
	v_add_f32_e32 v41, v41, v40
	v_add_u32_e32 v42, v180, v184
	v_sub_u32_e32 v207, 0, v218
	ds_write_b32 v42, v41 offset:32256
	v_add_f32_e32 v39, v39, v40
	v_add_u32_e32 v41, v180, v206
	v_sub_u32_e32 v208, 0, v219
	ds_write_b32 v41, v39 offset:32256
	v_add_f32_e32 v38, v38, v40
	v_add_u32_e32 v39, v180, v207
	v_sub_u32_e32 v209, 0, v220
	ds_write_b32 v39, v38 offset:32256
	v_add_f32_e32 v37, v37, v40
	v_add_u32_e32 v38, v180, v208
	ds_write_b32 v38, v37 offset:32256
	v_add_f32_e32 v36, v36, v40
	v_add_u32_e32 v37, v180, v209
	ds_write_b32 v37, v36 offset:32256
	s_waitcnt lgkmcnt(0)
	s_barrier
	ds_read_b128 v[36:39], v188
	ds_read_b128 v[40:43], v186 offset:15872
	ds_read_b128 v[44:47], v186 offset:15888
	ds_read_b128 v[48:51], v188 offset:16
	s_waitcnt lgkmcnt(2)
	v_sub_f32_e32 v53, v40, v36
	v_mul_f32_e32 v53, 0x3fb8aa3b, v53
	v_sub_f32_e32 v55, v41, v37
	v_sub_f32_e32 v52, v36, v40
	v_exp_f32_e32 v54, v53
	v_sub_f32_e32 v53, v37, v41
	v_mul_f32_e32 v55, 0x3fb8aa3b, v55
	v_mul_f32_e32 v36, 0x3fb8aa3b, v36
	v_mul_f32_e32 v37, 0x3fb8aa3b, v37
	v_sub_f32_e32 v57, v42, v38
	v_exp_f32_e32 v55, v55
	v_exp_f32_e32 v36, v36
	v_exp_f32_e32 v37, v37
	v_mul_f32_e32 v57, 0x3fb8aa3b, v57
	v_sub_f32_e32 v59, v43, v39
	v_sub_f32_e32 v56, v38, v42
	v_exp_f32_e32 v58, v57
	v_mul_f32_e32 v38, 0x3fb8aa3b, v38
	v_sub_f32_e32 v57, v39, v43
	v_mul_f32_e32 v59, 0x3fb8aa3b, v59
	v_mul_f32_e32 v39, 0x3fb8aa3b, v39
	v_exp_f32_e32 v38, v38
	v_exp_f32_e32 v59, v59
	v_exp_f32_e32 v39, v39
	v_pk_mul_f32 v[54:55], v[54:55], v[156:157]
	v_pk_mul_f32 v[156:157], v[158:159], v[36:37]
	s_waitcnt lgkmcnt(0)
	v_sub_f32_e32 v37, v44, v48
	v_mul_f32_e32 v37, 0x3fb8aa3b, v37
	v_pk_mul_f32 v[58:59], v[58:59], v[154:155]
	v_pk_mul_f32 v[154:155], v[162:163], v[38:39]
	v_sub_f32_e32 v36, v48, v44
	v_exp_f32_e32 v38, v37
	v_sub_f32_e32 v37, v49, v45
	v_mul_f32_e32 v52, 0x3fb8aa3b, v52
	v_mul_f32_e32 v53, 0x3fb8aa3b, v53
	v_mul_f32_e32 v36, 0x3fb8aa3b, v36
	v_mul_f32_e32 v37, 0x3fb8aa3b, v37
	v_exp_f32_e32 v52, v52
	v_exp_f32_e32 v53, v53
	v_exp_f32_e32 v36, v36
	v_exp_f32_e32 v37, v37
	v_sub_f32_e32 v39, v45, v49
	v_mul_f32_e32 v39, 0x3fb8aa3b, v39
	v_exp_f32_e32 v39, v39
	v_pk_mul_f32 v[52:53], v[158:159], v[52:53]
	v_pk_mul_f32 v[158:159], v[160:161], v[36:37]
	v_sub_f32_e32 v37, v46, v50
	v_mul_f32_e32 v37, 0x3fb8aa3b, v37
	v_pk_mul_f32 v[152:153], v[38:39], v[152:153]
	v_mul_f32_e32 v36, 0x3fb8aa3b, v49
	v_exp_f32_e32 v38, v37
	v_mul_f32_e32 v37, 0x3fb8aa3b, v50
	v_exp_f32_e32 v49, v36
	v_sub_f32_e32 v36, v50, v46
	v_exp_f32_e32 v50, v37
	v_sub_f32_e32 v37, v51, v47
	v_mul_f32_e32 v56, 0x3fb8aa3b, v56
	v_mul_f32_e32 v57, 0x3fb8aa3b, v57
	v_mul_f32_e32 v48, 0x3fb8aa3b, v48
	v_mul_f32_e32 v36, 0x3fb8aa3b, v36
	v_mul_f32_e32 v37, 0x3fb8aa3b, v37
	v_sub_f32_e32 v39, v47, v51
	v_exp_f32_e32 v56, v56
	v_exp_f32_e32 v57, v57
	v_exp_f32_e32 v48, v48
	v_exp_f32_e32 v36, v36
	v_exp_f32_e32 v37, v37
	v_mul_f32_e32 v39, 0x3fb8aa3b, v39
	v_exp_f32_e32 v39, v39
	v_mul_f32_e32 v51, 0x3fb8aa3b, v51
	v_exp_f32_e32 v51, v51
	v_pk_mul_f32 v[56:57], v[162:163], v[56:57]
	v_pk_mul_f32 v[48:49], v[160:161], v[48:49]
	v_pk_mul_f32 v[160:161], v[166:167], v[36:37]
	v_pk_mul_f32 v[150:151], v[38:39], v[150:151]
	v_cvt_pk_bf16_f32 v36, v52, v53
	v_cvt_pk_bf16_f32 v37, v56, v57
	v_cvt_pk_bf16_f32 v38, v158, v159
	v_cvt_pk_bf16_f32 v39, v160, v161
	v_pk_mul_f32 v[50:51], v[166:167], v[50:51]
	ds_write_b128 v185, v[36:39] offset:32768
	v_cvt_pk_bf16_f32 v36, v54, v55
	v_cvt_pk_bf16_f32 v37, v58, v59
	v_cvt_pk_bf16_f32 v38, v152, v153
	v_cvt_pk_bf16_f32 v39, v150, v151
	ds_write_b128 v185, v[36:39] offset:50176
	v_cvt_pk_bf16_f32 v36, v156, v157
	v_cvt_pk_bf16_f32 v37, v154, v155
	v_cvt_pk_bf16_f32 v38, v48, v49
	v_cvt_pk_bf16_f32 v39, v50, v51
	ds_write_b128 v8, v[36:39]
	ds_read_b128 v[36:39], v191
	ds_read_b128 v[48:51], v191 offset:16
	s_waitcnt lgkmcnt(1)
	v_sub_f32_e32 v52, v36, v40
	v_sub_f32_e32 v40, v40, v36
	v_sub_f32_e32 v53, v37, v41
	v_sub_f32_e32 v41, v41, v37
	v_mul_f32_e32 v36, 0x3fb8aa3b, v36
	v_mul_f32_e32 v37, 0x3fb8aa3b, v37
	v_exp_f32_e32 v36, v36
	v_exp_f32_e32 v37, v37
	v_sub_f32_e32 v54, v38, v42
	v_sub_f32_e32 v42, v42, v38
	v_mul_f32_e32 v38, 0x3fb8aa3b, v38
	v_sub_f32_e32 v55, v39, v43
	v_sub_f32_e32 v43, v43, v39
	v_mul_f32_e32 v39, 0x3fb8aa3b, v39
	v_exp_f32_e32 v38, v38
	v_exp_f32_e32 v39, v39
	v_pk_mul_f32 v[56:57], v[164:165], v[36:37]
	s_waitcnt lgkmcnt(0)
	v_sub_f32_e32 v37, v44, v48
	v_mul_f32_e32 v37, 0x3fb8aa3b, v37
	v_pk_mul_f32 v[58:59], v[170:171], v[38:39]
	v_sub_f32_e32 v36, v48, v44
	v_exp_f32_e32 v38, v37
	v_sub_f32_e32 v37, v49, v45
	v_mul_f32_e32 v42, 0x3fb8aa3b, v42
	v_mul_f32_e32 v43, 0x3fb8aa3b, v43
	v_mul_f32_e32 v36, 0x3fb8aa3b, v36
	v_mul_f32_e32 v37, 0x3fb8aa3b, v37
	v_exp_f32_e32 v42, v42
	v_exp_f32_e32 v43, v43
	v_exp_f32_e32 v36, v36
	v_exp_f32_e32 v37, v37
	v_sub_f32_e32 v39, v45, v49
	v_mul_f32_e32 v39, 0x3fb8aa3b, v39
	v_exp_f32_e32 v39, v39
	v_pk_mul_f32 v[42:43], v[42:43], v[146:147]
	v_pk_mul_f32 v[146:147], v[168:169], v[36:37]
	v_sub_f32_e32 v37, v46, v50
	v_mul_f32_e32 v37, 0x3fb8aa3b, v37
	v_pk_mul_f32 v[144:145], v[38:39], v[144:145]
	v_mul_f32_e32 v36, 0x3fb8aa3b, v49
	v_exp_f32_e32 v38, v37
	v_mul_f32_e32 v37, 0x3fb8aa3b, v50
	v_exp_f32_e32 v45, v36
	v_sub_f32_e32 v36, v50, v46
	v_exp_f32_e32 v46, v37
	v_sub_f32_e32 v37, v51, v47
	v_mul_f32_e32 v52, 0x3fb8aa3b, v52
	v_mul_f32_e32 v53, 0x3fb8aa3b, v53
	v_mul_f32_e32 v54, 0x3fb8aa3b, v54
	v_mul_f32_e32 v55, 0x3fb8aa3b, v55
	v_mul_f32_e32 v36, 0x3fb8aa3b, v36
	v_mul_f32_e32 v37, 0x3fb8aa3b, v37
	v_sub_f32_e32 v39, v47, v51
	v_exp_f32_e32 v52, v52
	v_mul_f32_e32 v40, 0x3fb8aa3b, v40
	v_exp_f32_e32 v53, v53
	v_mul_f32_e32 v41, 0x3fb8aa3b, v41
	v_exp_f32_e32 v54, v54
	v_exp_f32_e32 v55, v55
	v_exp_f32_e32 v36, v36
	v_exp_f32_e32 v37, v37
	v_mul_f32_e32 v39, 0x3fb8aa3b, v39
	v_exp_f32_e32 v40, v40
	v_exp_f32_e32 v41, v41
	v_mul_f32_e32 v44, 0x3fb8aa3b, v48
	v_exp_f32_e32 v39, v39
	v_mul_f32_e32 v47, 0x3fb8aa3b, v51
	v_exp_f32_e32 v44, v44
	v_exp_f32_e32 v47, v47
	v_pk_mul_f32 v[52:53], v[164:165], v[52:53]
	v_pk_mul_f32 v[54:55], v[170:171], v[54:55]
	v_pk_mul_f32 v[48:49], v[172:173], v[36:37]
	v_pk_mul_f32 v[40:41], v[40:41], v[148:149]
	v_pk_mul_f32 v[50:51], v[38:39], v[142:143]
	v_cvt_pk_bf16_f32 v36, v52, v53
	v_cvt_pk_bf16_f32 v37, v54, v55
	v_cvt_pk_bf16_f32 v38, v146, v147
	v_cvt_pk_bf16_f32 v39, v48, v49
	v_pk_mul_f32 v[44:45], v[168:169], v[44:45]
	v_pk_mul_f32 v[46:47], v[172:173], v[46:47]
	ds_write_b128 v185, v[36:39] offset:41472
	v_cvt_pk_bf16_f32 v36, v40, v41
	v_cvt_pk_bf16_f32 v37, v42, v43
	v_cvt_pk_bf16_f32 v38, v144, v145
	v_cvt_pk_bf16_f32 v39, v50, v51
	ds_write_b128 v185, v[36:39] offset:58880
	v_cvt_pk_bf16_f32 v36, v56, v57
	v_cvt_pk_bf16_f32 v37, v58, v59
	v_cvt_pk_bf16_f32 v38, v44, v45
	v_cvt_pk_bf16_f32 v39, v46, v47
	ds_write_b128 v8, v[36:39] offset:8704
	s_waitcnt lgkmcnt(0)
	s_barrier
	ds_read_b128 v[36:39], v192 offset:50176
	ds_read_b128 v[40:43], v193 offset:32768
	ds_read_b128 v[44:47], v193 offset:32832
	ds_read_b128 v[48:51], v192 offset:50240
	s_waitcnt lgkmcnt(2)
	v_mfma_f32_16x16x32_bf16 v[36:39], v[36:39], v[40:43], 0
	ds_read_b128 v[52:55], v192 offset:54528
	ds_read_b128 v[56:59], v192 offset:54592
	v_mul_u32_u24_e32 v8, 0x90, v131
	v_add_u32_e32 v8, v190, v8
	s_waitcnt lgkmcnt(2)
	v_mfma_f32_16x16x32_bf16 v[36:39], v[48:51], v[44:47], v[36:39]
	ds_read_b128 v[48:51], v192 offset:50304
	s_waitcnt lgkmcnt(2)
	v_mfma_f32_16x16x32_bf16 v[40:43], v[52:55], v[40:43], 0
	s_waitcnt lgkmcnt(1)
	v_mfma_f32_16x16x32_bf16 v[40:43], v[56:59], v[44:47], v[40:43]
	ds_read_b128 v[44:47], v193 offset:32896
	ds_read_b128 v[52:55], v193 offset:32960
	ds_read_b128 v[56:59], v192 offset:50368
	s_waitcnt lgkmcnt(2)
	v_mfma_f32_16x16x32_bf16 v[36:39], v[48:51], v[44:47], v[36:39]
	ds_read_b128 v[48:51], v192 offset:54656
	ds_read_b128 v[142:145], v192 offset:54720
	s_waitcnt lgkmcnt(1)
	v_mfma_f32_16x16x32_bf16 v[40:43], v[48:51], v[44:47], v[40:43]
	v_or_b32_e32 v45, 1, v194
	v_cmp_le_i32_e32 vcc, v189, v45
	v_mul_u32_u24_e32 v44, 0x220, v196
	v_mfma_f32_16x16x32_bf16 v[36:39], v[56:59], v[52:55], v[36:39]
	v_add_u32_e32 v127, v187, v44
	s_waitcnt lgkmcnt(0)
	v_mfma_f32_16x16x32_bf16 v[40:43], v[142:145], v[52:55], v[40:43]
	s_nop 4
	v_cndmask_b32_e32 v37, 0, v37, vcc
	v_cmp_le_i32_e32 vcc, v189, v197
	v_cndmask_b32_e64 v36, v36, 0, s[14:15]
	v_cvt_pk_bf16_f32 v36, v36, v37
	v_cndmask_b32_e32 v38, 0, v38, vcc
	v_cmp_le_i32_e32 vcc, v189, v198
	s_nop 1
	v_cndmask_b32_e32 v39, 0, v39, vcc
	v_cmp_le_i32_e32 vcc, v189, v199
	v_cvt_pk_bf16_f32 v37, v38, v39
	s_nop 0
	v_cndmask_b32_e32 v38, 0, v40, vcc
	v_cmp_le_i32_e32 vcc, v189, v200
	s_nop 1
	v_cndmask_b32_e32 v39, 0, v41, vcc
	v_cmp_le_i32_e32 vcc, v189, v202
	v_cvt_pk_bf16_f32 v38, v38, v39
	s_nop 0
	v_cndmask_b32_e32 v40, 0, v42, vcc
	v_cmp_le_i32_e32 vcc, v189, v203
	s_nop 1
	v_cndmask_b32_e32 v41, 0, v43, vcc
	v_cvt_pk_bf16_f32 v39, v40, v41
	ds_write2_b64 v195, v[36:37], v[38:39] offset1:4
	s_waitcnt lgkmcnt(0)
	s_barrier
	ds_read_b64_tr_b16 v[38:39], v127 offset:2176
	ds_read_b64_tr_b16 v[36:37], v127
	ds_read_b64_tr_b16 v[42:43], v127 offset:2184
	ds_read_b64_tr_b16 v[40:41], v127 offset:8
	ds_read_b128 v[44:47], v8
	ds_read_b128 v[48:51], v8 offset:64
	s_waitcnt lgkmcnt(1)
	v_mfma_f32_16x16x32_bf16 v[52:55], v[36:39], v[44:47], v[88:91]
	ds_read_b128 v[56:59], v8 offset:2304
	s_nop 1
	ds_read_b128 v[88:91], v8 offset:2368
	v_mfma_f32_16x16x32_bf16 v[44:47], v[40:43], v[44:47], v[92:95]
	s_waitcnt lgkmcnt(1)
	v_mfma_f32_16x16x32_bf16 v[80:83], v[36:39], v[56:59], v[80:83]
	v_mfma_f32_16x16x32_bf16 v[56:59], v[40:43], v[56:59], v[84:87]
	s_nop 2
	ds_read_b128 v[84:87], v8 offset:4608
	ds_read_b128 v[92:95], v8 offset:4672
	s_waitcnt lgkmcnt(1)
	v_mfma_f32_16x16x32_bf16 v[68:71], v[36:39], v[84:87], v[68:71]
	v_mfma_f32_16x16x32_bf16 v[76:79], v[40:43], v[84:87], v[76:79]
	ds_read_b128 v[84:87], v8 offset:6912
	ds_read_b128 v[142:145], v8 offset:6976
	v_mul_u32_u24_e32 v8, 0x110, v131
	v_add_u32_e32 v8, v201, v8
	s_waitcnt lgkmcnt(1)
	v_mfma_f32_16x16x32_bf16 v[36:39], v[36:39], v[84:87], v[64:67]
	s_nop 2
	ds_read_b64_tr_b16 v[64:65], v127 offset:17408
	ds_read_b64_tr_b16 v[66:67], v127 offset:19584
	v_mfma_f32_16x16x32_bf16 v[40:43], v[40:43], v[84:87], v[60:63]
	s_nop 2
	ds_read_b64_tr_b16 v[62:63], v127 offset:19592
	ds_read_b64_tr_b16 v[60:61], v127 offset:17416
	s_waitcnt lgkmcnt(2)
	v_mfma_f32_16x16x32_bf16 v[52:55], v[64:67], v[48:51], v[52:55]
	s_waitcnt lgkmcnt(0)
	v_mfma_f32_16x16x32_bf16 v[44:47], v[60:63], v[48:51], v[44:47]
	v_mfma_f32_16x16x32_bf16 v[48:51], v[64:67], v[88:91], v[80:83]
	v_mfma_f32_16x16x32_bf16 v[56:59], v[60:63], v[88:91], v[56:59]
	v_mfma_f32_16x16x32_bf16 v[68:71], v[64:67], v[92:95], v[68:71]
	v_mfma_f32_16x16x32_bf16 v[76:79], v[60:63], v[92:95], v[76:79]
	v_mfma_f32_16x16x32_bf16 v[36:39], v[64:67], v[142:145], v[36:39]
	v_mfma_f32_16x16x32_bf16 v[40:43], v[60:63], v[142:145], v[40:43]
	ds_read_b128 v[60:63], v8
	ds_read_b128 v[64:67], v8 offset:64
	s_waitcnt vmcnt(7) lgkmcnt(1)
	v_mfma_f32_16x16x32_bf16 v[52:55], v[116:119], v[60:63], v[52:55]
	s_waitcnt vmcnt(3)
	v_mfma_f32_16x16x32_bf16 v[44:47], v[120:123], v[60:63], v[44:47]
	ds_read_b128 v[60:63], v8 offset:4352
	ds_read_b128 v[80:83], v8 offset:4416
	s_waitcnt lgkmcnt(1)
	v_mfma_f32_16x16x32_bf16 v[48:51], v[116:119], v[60:63], v[48:51]
	v_mfma_f32_16x16x32_bf16 v[56:59], v[120:123], v[60:63], v[56:59]
	ds_read_b128 v[60:63], v8 offset:8704
	ds_read_b128 v[84:87], v8 offset:8768
	s_waitcnt lgkmcnt(1)
	v_mfma_f32_16x16x32_bf16 v[68:71], v[116:119], v[60:63], v[68:71]
	v_mfma_f32_16x16x32_bf16 v[60:63], v[120:123], v[60:63], v[76:79]
	s_nop 2
	ds_read_b128 v[76:79], v8 offset:13056
	ds_read_b128 v[88:91], v8 offset:13120
	s_waitcnt lgkmcnt(1)
	v_mfma_f32_16x16x32_bf16 v[36:39], v[116:119], v[76:79], v[36:39]
	v_mfma_f32_16x16x32_bf16 v[40:43], v[120:123], v[76:79], v[40:43]
	v_mfma_f32_16x16x32_bf16 v[52:55], v[108:111], v[64:67], v[52:55]
	s_waitcnt vmcnt(2)
	v_mfma_f32_16x16x32_bf16 v[44:47], v[112:115], v[64:67], v[44:47]
	v_mfma_f32_16x16x32_bf16 v[48:51], v[108:111], v[80:83], v[48:51]
	v_mfma_f32_16x16x32_bf16 v[56:59], v[112:115], v[80:83], v[56:59]
	v_mfma_f32_16x16x32_bf16 v[64:67], v[108:111], v[84:87], v[68:71]
	v_mfma_f32_16x16x32_bf16 v[60:63], v[112:115], v[84:87], v[60:63]
	s_waitcnt lgkmcnt(0)
	v_mfma_f32_16x16x32_bf16 v[36:39], v[108:111], v[88:91], v[36:39]
	v_mfma_f32_16x16x32_bf16 v[40:43], v[112:115], v[88:91], v[40:43]
	ds_read_b128 v[68:71], v8 offset:128
	ds_read_b128 v[76:79], v8 offset:192
	s_waitcnt lgkmcnt(1)
	v_mfma_f32_16x16x32_bf16 v[52:55], v[100:103], v[68:71], v[52:55]
	s_waitcnt vmcnt(1)
	v_mfma_f32_16x16x32_bf16 v[44:47], v[104:107], v[68:71], v[44:47]
	ds_read_b128 v[68:71], v8 offset:4480
	ds_read_b128 v[84:87], v8 offset:4544
	s_waitcnt lgkmcnt(1)
	v_mfma_f32_16x16x32_bf16 v[48:51], v[100:103], v[68:71], v[48:51]
	v_mfma_f32_16x16x32_bf16 v[56:59], v[104:107], v[68:71], v[56:59]
	ds_read_b128 v[68:71], v8 offset:8832
	ds_read_b128 v[88:91], v8 offset:8896
	s_waitcnt lgkmcnt(1)
	v_mfma_f32_16x16x32_bf16 v[92:95], v[100:103], v[68:71], v[64:67]
	v_mfma_f32_16x16x32_bf16 v[68:71], v[104:107], v[68:71], v[60:63]
	s_nop 2
	ds_read_b128 v[60:63], v8 offset:13184
	ds_read_b128 v[108:111], v8 offset:13248
	s_waitcnt lgkmcnt(1)
	v_mfma_f32_16x16x32_bf16 v[36:39], v[100:103], v[60:63], v[36:39]
	v_mfma_f32_16x16x32_bf16 v[100:103], v[104:107], v[60:63], v[40:43]
	v_mfma_f32_16x16x32_bf16 v[80:83], v[72:75], v[76:79], v[52:55]
	s_waitcnt vmcnt(0)
	v_mfma_f32_16x16x32_bf16 v[76:79], v[96:99], v[76:79], v[44:47]
	v_mfma_f32_16x16x32_bf16 v[64:67], v[72:75], v[84:87], v[48:51]
	v_mfma_f32_16x16x32_bf16 v[60:63], v[96:99], v[84:87], v[56:59]
	v_mfma_f32_16x16x32_bf16 v[52:55], v[72:75], v[88:91], v[92:95]
	v_mfma_f32_16x16x32_bf16 v[48:51], v[96:99], v[88:91], v[68:71]
	s_waitcnt lgkmcnt(0)
	v_mfma_f32_16x16x32_bf16 v[40:43], v[72:75], v[108:111], v[36:39]
	v_mfma_f32_16x16x32_bf16 v[36:39], v[96:99], v[108:111], v[100:103]
	s_add_i32 s76, s47, s22
	s_cmpk_gt_i32 s76, 0x3ff
	s_cbranch_scc1 .Lgcb_skip
	s_ashr_i32 s61, s76, 8
	s_add_i32 s61, s61, 4
	s_lshl_b32 s61, s61, 12
	s_and_b32 s62, s76, 63
	s_lshl_b32 s62, s62, 6
	s_or_b32 s61, s61, s62
	s_bfe_u32 s62, s76, 0x20006
	s_lshl_b32 s63, s62, 7
	s_mov_b32 s66, s20
	s_mov_b32 s67, 0
	v_and_b32_e32 v230, 48, v204
	v_mov_b32_e32 v231, 0
	v_and_b32_e32 v232, 15, v204
	s_lshl_b32 s78, s62, 8
	s_add_u32 s78, s16, s78
	s_addc_u32 s79, s17, 0
	v_lshlrev_b32_e32 v236, 4, v232
	v_mov_b32_e32 v237, 0
	v_lshl_add_u64 v[234:235], v[236:237], 0, s[78:79]
	v_lshrrev_b32_e32 v233, 4, v204
	v_or_b32_e32 v233, s61, v233
	v_mad_u64_u32 v[236:237], s[64:65], v233, s0, v[234:235]
	global_load_dwordx4 v[188:191], v[236:237], off
	global_load_dwordx4 v[192:195], v[236:237], off offset:1024
	v_or_b32_e32 v233, 32, v233
	v_mad_u64_u32 v[236:237], s[64:65], v233, s0, v[234:235]
	global_load_dwordx4 v[196:199], v[236:237], off
	global_load_dwordx4 v[200:203], v[236:237], off offset:1024
	v_mov_b64_e32 v[234:235], s[16:17]
	v_or_b32_e32 v233, s61, v232
	v_mad_u64_u32 v[236:237], s[64:65], v233, s0, v[234:235]
	v_lshl_add_u64 v[236:237], v[236:237], 0, v[230:231]
	v_lshl_add_u64 v[236:237], v[236:237], 0, s[66:67]
	global_load_dwordx4 v[206:209], v[236:237], off offset:2048
	v_or_b32_e32 v233, 16, v232
	v_or_b32_e32 v233, s61, v233
	v_mad_u64_u32 v[236:237], s[64:65], v233, s0, v[234:235]
	v_lshl_add_u64 v[236:237], v[236:237], 0, v[230:231]
	v_lshl_add_u64 v[236:237], v[236:237], 0, s[66:67]
	global_load_dwordx4 v[210:213], v[236:237], off offset:2048
	v_or_b32_e32 v233, 32, v232
	v_or_b32_e32 v233, s61, v233
	v_mad_u64_u32 v[236:237], s[64:65], v233, s0, v[234:235]
	v_lshl_add_u64 v[236:237], v[236:237], 0, v[230:231]
	v_lshl_add_u64 v[236:237], v[236:237], 0, s[66:67]
	global_load_dwordx4 v[214:217], v[236:237], off offset:2048
	v_or_b32_e32 v233, 48, v232
	v_or_b32_e32 v233, s61, v233
	v_mad_u64_u32 v[236:237], s[64:65], v233, s0, v[234:235]
	v_lshl_add_u64 v[236:237], v[236:237], 0, v[230:231]
	v_lshl_add_u64 v[236:237], v[236:237], 0, s[66:67]
	global_load_dwordx4 v[218:221], v[236:237], off offset:2048
	v_lshrrev_b32_e32 v233, 6, v204
	v_lshlrev_b32_e32 v233, 4, v233
	v_or_b32_e32 v236, s63, v232
	v_add_u32_e32 v236, v236, v233
	v_lshlrev_b32_e32 v236, 5, v236
	v_and_b32_e32 v233, 16, v204
	v_add_u32_e32 v236, v236, v233
	v_mov_b32_e32 v237, 0
	v_lshl_add_u64 v[236:237], v[236:237], 0, s[18:19]
	v_mov_b32_e32 v222, 0
	v_mov_b32_e32 v223, 0
	v_mov_b32_e32 v224, 0
	v_mov_b32_e32 v225, 0
	v_and_b32_e32 v233, 63, v204
	v_cmp_gt_u32_e32 vcc, 32, v233
	s_and_saveexec_b64 s[70:71], vcc
	global_load_dwordx4 v[222:225], v[236:237], off
	s_or_b64 exec, exec, s[70:71]
	s_lshl_b32 s63, s63, 2
	s_add_u32 s74, s24, s63
	s_addc_u32 s75, s25, 0
	v_lshrrev_b32_e32 v233, 6, v204
	v_lshlrev_b32_e32 v236, 6, v233
	v_bfe_u32 v233, v204, 4, 2
	v_lshl_add_u32 v236, v233, 4, v236
	v_mov_b32_e32 v237, 0
	v_lshl_add_u64 v[236:237], v[236:237], 0, s[74:75]
	global_load_dwordx4 v[226:229], v[236:237], off
